# counted/covered waits: the second lgkmcnt(0) drain right after each GEMM compute-segment barrier deleted (the identical drain sits in front of that barrier with no LDS op in between), on the scalar-re
# speedup vs baseline: 1.0051x; 1.0006x over previous
; #define PG8_STAGE(bufoff, gbase, voff) do { _Pragma("unroll") for (int _i = 0; _i < 2; ++_i) \
;         __builtin_amdgcn_global_load_lds((const unsigned*)((const char*)(gbase) + (voff)[_i]), (PG8_LAS unsigned*)(lds + (bufoff) + ldsw + _i * 8192), 16, 0, 0); } while (0)
; #define PG8_LDA(dst, b, h) do { _Pragma("unroll") for (int m = 0; m < 4; ++m) _Pragma("unroll") for (int k = 0; k < 2; ++k) dst[m][k] = *(const PG8_LAS bf16x8*)(lds + PG8_SA(b, h) + aoff + m * 2048 + k * 1024); } while (0)
; #define PG8_LDB(dst, b, h) do { _Pragma("unroll") for (int n = 0; n < 2; ++n) _Pragma("unroll") for (int k = 0; k < 2; ++k) dst[n][k] = *(const PG8_LAS bf16x8*)(lds + PG8_SB(b, h) + boff + n * 2048 + k * 1024); } while (0)
; #define PG8_MMA(ai, bj, At, Bt) do { __builtin_amdgcn_s_setprio(1); _Pragma("unroll") for (int m = 0; m < 4; ++m) _Pragma("unroll") for (int n = 0; n < 2; ++n) _Pragma("unroll") for (int k = 0; k < 2; ++k) \
;         acc[ai][bj][m][n] = __builtin_amdgcn_mfma_f32_16x16x32_bf16(Bt[n][k], At[m][k], acc[ai][bj][m][n], 0, 0, 0); __builtin_amdgcn_s_setprio(0); } while (0)
; #define PG8_WAIT_V(n) asm volatile("s_waitcnt vmcnt(" #n ")" ::: "memory")
; #define PG8_WAIT_L(n) asm volatile("s_waitcnt lgkmcnt(" #n ")" ::: "memory")
; #define PG8_BAR __builtin_amdgcn_s_barrier()
; #define PG8_SCHED __builtin_amdgcn_sched_barrier(0)
; template <class Epi, class Sched, bool ALIGN_EPI = false, bool SP2 = false>
; __device__ __forceinline__ void gemm_phase(PG8_LAS unsigned char* lds, const Gemm g, const Sched& S, const Epi& E, int wid0) {
;     ...
;             const bool last = (t == nt - 2);
;             const char* a1 = cA + (size_t)(t + 1) * kstep;
;             const char* a2 = last ? nA : cA + (size_t)(t + 2) * kstep; const char* b2 = last ? nB : cB + (size_t)(t + 2) * kstep;
;             const char* a3 = a2 + kstep; const char* b3 = b2 + kstep;
;             if (last && has_next) S.a_ready(nxt);
;             if constexpr (SP2) {
;             PG8_LDB(B0, 0, 0); PG8_LDB(B1, 0, 1); PG8_SCHED; PG8_LDA(At, 0, 0); PG8_STAGE(PG8_SA(1, 1), a1 + hstep, voffA);
;             PG8_WAIT_V(8); PG8_WAIT_L(0); PG8_BAR; PG8_MMA(0, 0, At, B0); PG8_MMA(0, 1, At, B1); PG8_BAR; PG8_SCHED;
;             PG8_LDA(At, 0, 1); PG8_STAGE(PG8_SB(0, 0), b2, voffB); PG8_STAGE(PG8_SB(0, 1), b2 + hstep, voffB); PG8_STAGE(PG8_SA(0, 0), a2, voffA);
.LBB0_143:
	s_add_i32 s65, 0, 0x10000
	s_add_i32 s66, 0, 0x14000
	v_add_u32_e32 v140, s65, v164
	v_add_u32_e32 v162, s66, v164
	ds_read_b128 v[128:131], v140
	ds_read_b128 v[132:135], v140 offset:1024
	ds_read_b128 v[136:139], v140 offset:2048
	ds_read_b128 v[140:143], v140 offset:3072
	ds_read_b128 v[158:161], v162
	ds_read_b128 v[166:169], v162 offset:1024
	ds_read_b128 v[170:173], v162 offset:2048
	ds_read_b128 v[174:177], v162 offset:3072
	v_lshl_add_u64 v[162:163], s[84:85], 0, v[156:157]
	s_add_i32 m0, s94, 0xc000
	ds_read_b128 v[178:181], v165
	ds_read_b128 v[182:185], v165 offset:1024
	ds_read_b128 v[186:189], v165 offset:2048
	ds_read_b128 v[198:201], v165 offset:3072
	ds_read_b128 v[202:205], v165 offset:4096
	ds_read_b128 v[206:209], v165 offset:5120
	ds_read_b128 v[210:213], v165 offset:6144
	ds_read_b128 v[220:223], v165 offset:7168
	global_load_lds_dwordx4 v[162:163], off
	v_lshl_add_u64 v[162:163], s[84:85], 0, v[154:155]
	s_add_i32 m0, s94, 0xe000
	s_nop 0
	global_load_lds_dwordx4 v[162:163], off
	s_add_u32 s26, s84, 0xfffc0080
	s_addc_u32 s27, s85, -1
	s_cmp_eq_u32 s64, 12
	s_cselect_b32 vcc_hi, s45, s27
	s_cselect_b32 vcc_lo, s77, s26
	s_cselect_b32 s87, s75, s11
	s_cselect_b32 s86, s83, s10
	s_waitcnt vmcnt(8)
	s_waitcnt lgkmcnt(0)
	s_barrier
	s_setprio 1
	v_mfma_f32_16x16x32_bf16 v[124:127], v[128:131], v[178:181], v[124:127]
	v_mfma_f32_16x16x32_bf16 v[120:123], v[136:139], v[178:181], v[120:123]
	v_mfma_f32_16x16x32_bf16 v[108:111], v[128:131], v[186:189], v[108:111]
	v_mfma_f32_16x16x32_bf16 v[104:107], v[136:139], v[186:189], v[104:107]
	v_mfma_f32_16x16x32_bf16 v[92:95], v[128:131], v[202:205], v[92:95]
	v_mfma_f32_16x16x32_bf16 v[88:91], v[136:139], v[202:205], v[88:91]
	v_mfma_f32_16x16x32_bf16 v[76:79], v[128:131], v[210:213], v[76:79]
	v_mfma_f32_16x16x32_bf16 v[72:75], v[136:139], v[210:213], v[72:75]
	v_mfma_f32_16x16x32_bf16 v[124:127], v[132:135], v[182:185], v[124:127]
	v_mfma_f32_16x16x32_bf16 v[120:123], v[140:143], v[182:185], v[120:123]
	v_mfma_f32_16x16x32_bf16 v[108:111], v[132:135], v[198:201], v[108:111]
	v_mfma_f32_16x16x32_bf16 v[104:107], v[140:143], v[198:201], v[104:107]
	v_mfma_f32_16x16x32_bf16 v[92:95], v[132:135], v[206:209], v[92:95]
	v_mfma_f32_16x16x32_bf16 v[88:91], v[140:143], v[206:209], v[88:91]
	v_mfma_f32_16x16x32_bf16 v[76:79], v[132:135], v[220:223], v[76:79]
	v_mfma_f32_16x16x32_bf16 v[72:75], v[140:143], v[220:223], v[72:75]
	s_setprio 0
	s_setprio 1
	v_mfma_f32_16x16x32_bf16 v[116:119], v[158:161], v[178:181], v[116:119]
	v_mfma_f32_16x16x32_bf16 v[112:115], v[170:173], v[178:181], v[112:115]
	v_mfma_f32_16x16x32_bf16 v[100:103], v[158:161], v[186:189], v[100:103]
	v_mfma_f32_16x16x32_bf16 v[96:99], v[170:173], v[186:189], v[96:99]
	v_mfma_f32_16x16x32_bf16 v[84:87], v[158:161], v[202:205], v[84:87]
	v_mfma_f32_16x16x32_bf16 v[80:83], v[170:173], v[202:205], v[80:83]
	v_mfma_f32_16x16x32_bf16 v[68:71], v[158:161], v[210:213], v[68:71]
	v_mfma_f32_16x16x32_bf16 v[64:67], v[170:173], v[210:213], v[64:67]
	v_mfma_f32_16x16x32_bf16 v[116:119], v[166:169], v[182:185], v[116:119]
	v_mfma_f32_16x16x32_bf16 v[112:115], v[174:177], v[182:185], v[112:115]
	v_mfma_f32_16x16x32_bf16 v[100:103], v[166:169], v[198:201], v[100:103]
	v_mfma_f32_16x16x32_bf16 v[96:99], v[174:177], v[198:201], v[96:99]
	v_mfma_f32_16x16x32_bf16 v[84:87], v[166:169], v[206:209], v[84:87]
	v_mfma_f32_16x16x32_bf16 v[80:83], v[174:177], v[206:209], v[80:83]
	v_mfma_f32_16x16x32_bf16 v[68:71], v[166:169], v[220:223], v[68:71]
	v_mfma_f32_16x16x32_bf16 v[64:67], v[174:177], v[220:223], v[64:67]
	s_barrier
	s_setprio 0
	s_add_i32 s26, s65, s93
	v_lshl_add_u64 v[162:163], s[86:87], 0, v[148:149]
	s_mov_b32 m0, s26
	ds_read_b128 v[178:181], v165 offset:16384
	ds_read_b128 v[182:185], v165 offset:17408
	ds_read_b128 v[186:189], v165 offset:18432
	ds_read_b128 v[198:201], v165 offset:19456
	ds_read_b128 v[202:205], v165 offset:20480
	ds_read_b128 v[206:209], v165 offset:21504
	ds_read_b128 v[210:213], v165 offset:22528
	ds_read_b128 v[220:223], v165 offset:23552
	global_load_lds_dwordx4 v[162:163], off
	s_add_i32 m0, s26, 0x2000
	s_add_u32 s26, s86, 0x40000
	v_lshl_add_u64 v[190:191], s[86:87], 0, v[144:145]
	s_addc_u32 s27, s87, 0
	s_add_i32 s65, s66, s93
	global_load_lds_dwordx4 v[190:191], off
	v_lshl_add_u64 v[194:195], s[26:27], 0, v[148:149]
	s_mov_b32 m0, s65
	v_lshl_add_u64 v[196:197], vcc, 0, v[146:147]
	global_load_lds_dwordx4 v[194:195], off
	v_lshl_add_u64 v[194:195], s[26:27], 0, v[144:145]
	s_add_i32 m0, s65, 0x2000
	s_nop 0
	global_load_lds_dwordx4 v[194:195], off
	v_lshl_add_u64 v[194:195], vcc, 0, v[150:151]
	s_mov_b32 m0, s94
	s_nop 0
	global_load_lds_dwordx4 v[194:195], off
	s_mov_b32 m0, s95
	s_nop 0
	global_load_lds_dwordx4 v[196:197], off
	s_waitcnt vmcnt(8)
	s_waitcnt lgkmcnt(0)
	s_barrier
; #define PG8_STAGE(bufoff, gbase, voff) do { _Pragma("unroll") for (int _i = 0; _i < 2; ++_i) \
;         __builtin_amdgcn_global_load_lds((const unsigned*)((const char*)(gbase) + (voff)[_i]), (PG8_LAS unsigned*)(lds + (bufoff) + ldsw + _i * 8192), 16, 0, 0); } while (0)
; #define PG8_LDA(dst, b, h) do { _Pragma("unroll") for (int m = 0; m < 4; ++m) _Pragma("unroll") for (int k = 0; k < 2; ++k) dst[m][k] = *(const PG8_LAS bf16x8*)(lds + PG8_SA(b, h) + aoff + m * 2048 + k * 1024); } while (0)
; #define PG8_LDB(dst, b, h) do { _Pragma("unroll") for (int n = 0; n < 2; ++n) _Pragma("unroll") for (int k = 0; k < 2; ++k) dst[n][k] = *(const PG8_LAS bf16x8*)(lds + PG8_SB(b, h) + boff + n * 2048 + k * 1024); } while (0)
; #define PG8_MMA(ai, bj, At, Bt) do { __builtin_amdgcn_s_setprio(1); _Pragma("unroll") for (int m = 0; m < 4; ++m) _Pragma("unroll") for (int n = 0; n < 2; ++n) _Pragma("unroll") for (int k = 0; k < 2; ++k) \
;         acc[ai][bj][m][n] = __builtin_amdgcn_mfma_f32_16x16x32_bf16(Bt[n][k], At[m][k], acc[ai][bj][m][n], 0, 0, 0); __builtin_amdgcn_s_setprio(0); } while (0)
; #define PG8_WAIT_V(n) asm volatile("s_waitcnt vmcnt(" #n ")" ::: "memory")
; #define PG8_WAIT_L(n) asm volatile("s_waitcnt lgkmcnt(" #n ")" ::: "memory")
; #define PG8_BAR __builtin_amdgcn_s_barrier()
; #define PG8_SCHED __builtin_amdgcn_sched_barrier(0)
; template <class Epi, class Sched, bool ALIGN_EPI = false, bool SP2 = false>
; __device__ __forceinline__ void gemm_phase(PG8_LAS unsigned char* lds, const Gemm g, const Sched& S, const Epi& E, int wid0) {
;     ...
;             PG8_WAIT_V(8); PG8_WAIT_L(0); PG8_BAR; PG8_MMA(1, 0, At, B0); PG8_MMA(1, 1, At, B1); PG8_BAR; PG8_SCHED;
;             PG8_LDB(B0, 1, 0); PG8_LDB(B1, 1, 1); PG8_SCHED; PG8_LDA(At, 1, 0); PG8_STAGE(PG8_SA(0, 1), a2 + hstep, voffA);
;             PG8_WAIT_V(8); PG8_WAIT_L(0); PG8_BAR; PG8_MMA(0, 0, At, B0); PG8_MMA(0, 1, At, B1); PG8_BAR; PG8_SCHED;
	s_setprio 1
	v_mfma_f32_16x16x32_bf16 v[60:63], v[128:131], v[178:181], v[60:63]
	v_mfma_f32_16x16x32_bf16 v[56:59], v[136:139], v[178:181], v[56:59]
	v_mfma_f32_16x16x32_bf16 v[44:47], v[128:131], v[186:189], v[44:47]
	v_mfma_f32_16x16x32_bf16 v[40:43], v[136:139], v[186:189], v[40:43]
	v_mfma_f32_16x16x32_bf16 v[28:31], v[128:131], v[202:205], v[28:31]
	v_mfma_f32_16x16x32_bf16 v[24:27], v[136:139], v[202:205], v[24:27]
	v_mfma_f32_16x16x32_bf16 v[12:15], v[128:131], v[210:213], v[12:15]
	v_mfma_f32_16x16x32_bf16 v[8:11], v[136:139], v[210:213], v[8:11]
	v_mfma_f32_16x16x32_bf16 v[60:63], v[132:135], v[182:185], v[60:63]
	v_mfma_f32_16x16x32_bf16 v[56:59], v[140:143], v[182:185], v[56:59]
	v_mfma_f32_16x16x32_bf16 v[44:47], v[132:135], v[198:201], v[44:47]
	v_mfma_f32_16x16x32_bf16 v[40:43], v[140:143], v[198:201], v[40:43]
	v_mfma_f32_16x16x32_bf16 v[28:31], v[132:135], v[206:209], v[28:31]
	v_mfma_f32_16x16x32_bf16 v[24:27], v[140:143], v[206:209], v[24:27]
	v_mfma_f32_16x16x32_bf16 v[12:15], v[132:135], v[220:223], v[12:15]
	v_mfma_f32_16x16x32_bf16 v[8:11], v[140:143], v[220:223], v[8:11]
	s_setprio 0
	s_setprio 1
	v_mfma_f32_16x16x32_bf16 v[52:55], v[158:161], v[178:181], v[52:55]
	v_mfma_f32_16x16x32_bf16 v[48:51], v[170:173], v[178:181], v[48:51]
	v_mfma_f32_16x16x32_bf16 v[36:39], v[158:161], v[186:189], v[36:39]
	v_mfma_f32_16x16x32_bf16 v[32:35], v[170:173], v[186:189], v[32:35]
	v_mfma_f32_16x16x32_bf16 v[20:23], v[158:161], v[202:205], v[20:23]
	v_mfma_f32_16x16x32_bf16 v[16:19], v[170:173], v[202:205], v[16:19]
	v_mfma_f32_16x16x32_bf16 v[4:7], v[158:161], v[210:213], v[4:7]
	v_mfma_f32_16x16x32_bf16 v[0:3], v[170:173], v[210:213], v[0:3]
	v_mfma_f32_16x16x32_bf16 v[52:55], v[166:169], v[182:185], v[52:55]
	v_mfma_f32_16x16x32_bf16 v[48:51], v[174:177], v[182:185], v[48:51]
	v_mfma_f32_16x16x32_bf16 v[36:39], v[166:169], v[198:201], v[36:39]
	v_mfma_f32_16x16x32_bf16 v[32:35], v[174:177], v[198:201], v[32:35]
	v_mfma_f32_16x16x32_bf16 v[20:23], v[166:169], v[206:209], v[20:23]
	v_mfma_f32_16x16x32_bf16 v[16:19], v[174:177], v[206:209], v[16:19]
	v_mfma_f32_16x16x32_bf16 v[4:7], v[166:169], v[220:223], v[4:7]
	v_mfma_f32_16x16x32_bf16 v[0:3], v[174:177], v[220:223], v[0:3]
	s_barrier
	s_setprio 0
	s_add_i32 s65, 0, 0x18000
	s_add_i32 s66, 0, 0x1c000
	v_add_u32_e32 v140, s65, v164
	v_add_u32_e32 v174, s66, v164
	ds_read_b128 v[128:131], v140
	ds_read_b128 v[132:135], v140 offset:1024
	ds_read_b128 v[136:139], v140 offset:2048
	ds_read_b128 v[140:143], v140 offset:3072
	ds_read_b128 v[158:161], v174
	ds_read_b128 v[166:169], v174 offset:1024
	ds_read_b128 v[170:173], v174 offset:2048
	ds_read_b128 v[174:177], v174 offset:3072
	s_add_u32 s26, vcc_lo, 0x40000
	s_addc_u32 s27, vcc_hi, 0
	s_mov_b32 m0, s96
	v_lshl_add_u64 v[214:215], s[26:27], 0, v[150:151]
	ds_read_b128 v[178:181], v165 offset:32768
	ds_read_b128 v[182:185], v165 offset:33792
	ds_read_b128 v[186:189], v165 offset:34816
	ds_read_b128 v[198:201], v165 offset:35840
	ds_read_b128 v[202:205], v165 offset:36864
	ds_read_b128 v[206:209], v165 offset:37888
	ds_read_b128 v[210:213], v165 offset:38912
	ds_read_b128 v[220:223], v165 offset:39936
	global_load_lds_dwordx4 v[214:215], off
	v_lshl_add_u64 v[214:215], s[26:27], 0, v[146:147]
	s_mov_b32 m0, s97
	s_nop 0
	global_load_lds_dwordx4 v[214:215], off
	s_waitcnt vmcnt(8)
	s_waitcnt lgkmcnt(0)
	s_barrier
	s_setprio 1
	v_mfma_f32_16x16x32_bf16 v[124:127], v[128:131], v[178:181], v[124:127]
	v_mfma_f32_16x16x32_bf16 v[120:123], v[136:139], v[178:181], v[120:123]
	v_mfma_f32_16x16x32_bf16 v[108:111], v[128:131], v[186:189], v[108:111]
	v_mfma_f32_16x16x32_bf16 v[104:107], v[136:139], v[186:189], v[104:107]
	v_mfma_f32_16x16x32_bf16 v[92:95], v[128:131], v[202:205], v[92:95]
	v_mfma_f32_16x16x32_bf16 v[88:91], v[136:139], v[202:205], v[88:91]
	v_mfma_f32_16x16x32_bf16 v[76:79], v[128:131], v[210:213], v[76:79]
	v_mfma_f32_16x16x32_bf16 v[72:75], v[136:139], v[210:213], v[72:75]
	v_mfma_f32_16x16x32_bf16 v[124:127], v[132:135], v[182:185], v[124:127]
	v_mfma_f32_16x16x32_bf16 v[120:123], v[140:143], v[182:185], v[120:123]
	v_mfma_f32_16x16x32_bf16 v[108:111], v[132:135], v[198:201], v[108:111]
	v_mfma_f32_16x16x32_bf16 v[104:107], v[140:143], v[198:201], v[104:107]
	v_mfma_f32_16x16x32_bf16 v[92:95], v[132:135], v[206:209], v[92:95]
	v_mfma_f32_16x16x32_bf16 v[88:91], v[140:143], v[206:209], v[88:91]
	v_mfma_f32_16x16x32_bf16 v[76:79], v[132:135], v[220:223], v[76:79]
	v_mfma_f32_16x16x32_bf16 v[72:75], v[140:143], v[220:223], v[72:75]
	s_setprio 0
	s_setprio 1
	v_mfma_f32_16x16x32_bf16 v[116:119], v[158:161], v[178:181], v[116:119]
	v_mfma_f32_16x16x32_bf16 v[112:115], v[170:173], v[178:181], v[112:115]
	v_mfma_f32_16x16x32_bf16 v[100:103], v[158:161], v[186:189], v[100:103]
	v_mfma_f32_16x16x32_bf16 v[96:99], v[170:173], v[186:189], v[96:99]
	v_mfma_f32_16x16x32_bf16 v[84:87], v[158:161], v[202:205], v[84:87]
	v_mfma_f32_16x16x32_bf16 v[80:83], v[170:173], v[202:205], v[80:83]
	v_mfma_f32_16x16x32_bf16 v[68:71], v[158:161], v[210:213], v[68:71]
	v_mfma_f32_16x16x32_bf16 v[64:67], v[170:173], v[210:213], v[64:67]
	v_mfma_f32_16x16x32_bf16 v[116:119], v[166:169], v[182:185], v[116:119]
	v_mfma_f32_16x16x32_bf16 v[112:115], v[174:177], v[182:185], v[112:115]
	v_mfma_f32_16x16x32_bf16 v[100:103], v[166:169], v[198:201], v[100:103]
	v_mfma_f32_16x16x32_bf16 v[96:99], v[174:177], v[198:201], v[96:99]
	v_mfma_f32_16x16x32_bf16 v[84:87], v[166:169], v[206:209], v[84:87]
	v_mfma_f32_16x16x32_bf16 v[80:83], v[174:177], v[206:209], v[80:83]
	v_mfma_f32_16x16x32_bf16 v[68:71], v[166:169], v[220:223], v[68:71]
	v_mfma_f32_16x16x32_bf16 v[64:67], v[174:177], v[220:223], v[64:67]
	s_barrier
; #define PG8_STAGE(bufoff, gbase, voff) do { _Pragma("unroll") for (int _i = 0; _i < 2; ++_i) \
;         __builtin_amdgcn_global_load_lds((const unsigned*)((const char*)(gbase) + (voff)[_i]), (PG8_LAS unsigned*)(lds + (bufoff) + ldsw + _i * 8192), 16, 0, 0); } while (0)
; #define PG8_LDA(dst, b, h) do { _Pragma("unroll") for (int m = 0; m < 4; ++m) _Pragma("unroll") for (int k = 0; k < 2; ++k) dst[m][k] = *(const PG8_LAS bf16x8*)(lds + PG8_SA(b, h) + aoff + m * 2048 + k * 1024); } while (0)
; #define PG8_MMA(ai, bj, At, Bt) do { __builtin_amdgcn_s_setprio(1); _Pragma("unroll") for (int m = 0; m < 4; ++m) _Pragma("unroll") for (int n = 0; n < 2; ++n) _Pragma("unroll") for (int k = 0; k < 2; ++k) \
;         acc[ai][bj][m][n] = __builtin_amdgcn_mfma_f32_16x16x32_bf16(Bt[n][k], At[m][k], acc[ai][bj][m][n], 0, 0, 0); __builtin_amdgcn_s_setprio(0); } while (0)
; #define PG8_WAIT_V(n) asm volatile("s_waitcnt vmcnt(" #n ")" ::: "memory")
; #define PG8_WAIT_L(n) asm volatile("s_waitcnt lgkmcnt(" #n ")" ::: "memory")
; #define PG8_BAR __builtin_amdgcn_s_barrier()
; #define PG8_SCHED __builtin_amdgcn_sched_barrier(0)
; template <class Epi, class Sched, bool ALIGN_EPI = false, bool SP2 = false>
; __device__ __forceinline__ void gemm_phase(PG8_LAS unsigned char* lds, const Gemm g, const Sched& S, const Epi& E, int wid0) {
;     ...
;             PG8_LDA(At, 1, 1); PG8_STAGE(PG8_SB(1, 0), b3, voffB); PG8_STAGE(PG8_SB(1, 1), b3 + hstep, voffB); PG8_STAGE(PG8_SA(1, 0), a3, voffA);
;             PG8_WAIT_V(8); PG8_WAIT_L(0); PG8_BAR; PG8_MMA(1, 0, At, B0); PG8_MMA(1, 1, At, B1); PG8_BAR; PG8_SCHED;
;     ...
;         if constexpr (ALIGN_EPI) { if (wr == 0) PG8_BAR; }
	s_setprio 0
	s_add_i32 s26, s65, s93
	v_lshl_add_u64 v[162:163], v[162:163], 0, s[30:31]
	s_mov_b32 m0, s26
	ds_read_b128 v[178:181], v165 offset:49152
	ds_read_b128 v[182:185], v165 offset:50176
	ds_read_b128 v[186:189], v165 offset:51200
	ds_read_b128 v[198:201], v165 offset:52224
	ds_read_b128 v[202:205], v165 offset:53248
	ds_read_b128 v[206:209], v165 offset:54272
	ds_read_b128 v[210:213], v165 offset:55296
	ds_read_b128 v[220:223], v165 offset:56320
	global_load_lds_dwordx4 v[162:163], off
	s_add_i32 m0, s26, 0x2000
	s_add_u32 s26, s86, 0x40080
	v_lshl_add_u64 v[162:163], v[190:191], 0, s[30:31]
	s_addc_u32 s27, s87, 0
	s_add_i32 s65, s66, s93
	global_load_lds_dwordx4 v[162:163], off
	v_lshl_add_u64 v[162:163], s[26:27], 0, v[148:149]
	s_mov_b32 m0, s65
	s_nop 0
	global_load_lds_dwordx4 v[162:163], off
	v_lshl_add_u64 v[162:163], s[26:27], 0, v[144:145]
	s_add_i32 m0, s65, 0x2000
	s_nop 0
	global_load_lds_dwordx4 v[162:163], off
	v_lshl_add_u64 v[162:163], v[194:195], 0, s[30:31]
	s_mov_b32 m0, s4
	s_nop 0
	global_load_lds_dwordx4 v[162:163], off
	v_lshl_add_u64 v[162:163], v[196:197], 0, s[30:31]
	s_mov_b32 m0, s5
	s_nop 0
	global_load_lds_dwordx4 v[162:163], off
	s_waitcnt vmcnt(8)
	s_waitcnt lgkmcnt(0)
	s_barrier
	s_setprio 1
	v_mfma_f32_16x16x32_bf16 v[60:63], v[128:131], v[178:181], v[60:63]
	v_mfma_f32_16x16x32_bf16 v[56:59], v[136:139], v[178:181], v[56:59]
	v_mfma_f32_16x16x32_bf16 v[44:47], v[128:131], v[186:189], v[44:47]
	v_mfma_f32_16x16x32_bf16 v[40:43], v[136:139], v[186:189], v[40:43]
	v_mfma_f32_16x16x32_bf16 v[28:31], v[128:131], v[202:205], v[28:31]
	v_mfma_f32_16x16x32_bf16 v[24:27], v[136:139], v[202:205], v[24:27]
	v_mfma_f32_16x16x32_bf16 v[12:15], v[128:131], v[210:213], v[12:15]
	v_mfma_f32_16x16x32_bf16 v[8:11], v[136:139], v[210:213], v[8:11]
	v_mfma_f32_16x16x32_bf16 v[60:63], v[132:135], v[182:185], v[60:63]
	v_mfma_f32_16x16x32_bf16 v[56:59], v[140:143], v[182:185], v[56:59]
	v_mfma_f32_16x16x32_bf16 v[44:47], v[132:135], v[198:201], v[44:47]
	v_mfma_f32_16x16x32_bf16 v[40:43], v[140:143], v[198:201], v[40:43]
	v_mfma_f32_16x16x32_bf16 v[28:31], v[132:135], v[206:209], v[28:31]
	v_mfma_f32_16x16x32_bf16 v[24:27], v[140:143], v[206:209], v[24:27]
	v_mfma_f32_16x16x32_bf16 v[12:15], v[132:135], v[220:223], v[12:15]
	v_mfma_f32_16x16x32_bf16 v[8:11], v[140:143], v[220:223], v[8:11]
	s_setprio 0
	s_setprio 1
	v_mfma_f32_16x16x32_bf16 v[52:55], v[158:161], v[178:181], v[52:55]
	v_mfma_f32_16x16x32_bf16 v[48:51], v[170:173], v[178:181], v[48:51]
	v_mfma_f32_16x16x32_bf16 v[36:39], v[158:161], v[186:189], v[36:39]
	v_mfma_f32_16x16x32_bf16 v[32:35], v[170:173], v[186:189], v[32:35]
	v_mfma_f32_16x16x32_bf16 v[20:23], v[158:161], v[202:205], v[20:23]
	v_mfma_f32_16x16x32_bf16 v[16:19], v[170:173], v[202:205], v[16:19]
	v_mfma_f32_16x16x32_bf16 v[4:7], v[158:161], v[210:213], v[4:7]
	v_mfma_f32_16x16x32_bf16 v[0:3], v[170:173], v[210:213], v[0:3]
	v_mfma_f32_16x16x32_bf16 v[52:55], v[166:169], v[182:185], v[52:55]
	v_mfma_f32_16x16x32_bf16 v[48:51], v[174:177], v[182:185], v[48:51]
	v_mfma_f32_16x16x32_bf16 v[36:39], v[166:169], v[198:201], v[36:39]
	v_mfma_f32_16x16x32_bf16 v[32:35], v[174:177], v[198:201], v[32:35]
	v_mfma_f32_16x16x32_bf16 v[20:23], v[166:169], v[206:209], v[20:23]
	v_mfma_f32_16x16x32_bf16 v[16:19], v[174:177], v[206:209], v[16:19]
	v_mfma_f32_16x16x32_bf16 v[4:7], v[166:169], v[220:223], v[4:7]
	v_mfma_f32_16x16x32_bf16 v[0:3], v[174:177], v[220:223], v[0:3]
	s_barrier
	s_setprio 0
	s_add_i32 s64, s64, 2
	s_add_u32 s10, s10, 0x100
	s_addc_u32 s11, s11, 0
	s_add_u32 s84, s84, 0x100
	s_addc_u32 s85, s85, 0
	s_cmp_gt_u32 s64, 13
	s_cbranch_scc0 .LBB0_143
	s_and_b64 vcc, exec, s[72:73]
	s_cbranch_vccz .LBB0_146
	s_barrier

; #define PG8_STAGE(bufoff, gbase, voff) do { _Pragma("unroll") for (int _i = 0; _i < 2; ++_i) \
;         __builtin_amdgcn_global_load_lds((const unsigned*)((const char*)(gbase) + (voff)[_i]), (PG8_LAS unsigned*)(lds + (bufoff) + ldsw + _i * 8192), 16, 0, 0); } while (0)
; #define PG8_LDA(dst, b, h) do { _Pragma("unroll") for (int m = 0; m < 4; ++m) _Pragma("unroll") for (int k = 0; k < 2; ++k) dst[m][k] = *(const PG8_LAS bf16x8*)(lds + PG8_SA(b, h) + aoff + m * 2048 + k * 1024); } while (0)
; #define PG8_LDB(dst, b, h) do { _Pragma("unroll") for (int n = 0; n < 2; ++n) _Pragma("unroll") for (int k = 0; k < 2; ++k) dst[n][k] = *(const PG8_LAS bf16x8*)(lds + PG8_SB(b, h) + boff + n * 2048 + k * 1024); } while (0)
; #define PG8_MMA(ai, bj, At, Bt) do { __builtin_amdgcn_s_setprio(1); _Pragma("unroll") for (int m = 0; m < 4; ++m) _Pragma("unroll") for (int n = 0; n < 2; ++n) _Pragma("unroll") for (int k = 0; k < 2; ++k) \
;         acc[ai][bj][m][n] = __builtin_amdgcn_mfma_f32_16x16x32_bf16(Bt[n][k], At[m][k], acc[ai][bj][m][n], 0, 0, 0); __builtin_amdgcn_s_setprio(0); } while (0)
; #define PG8_WAIT_V(n) asm volatile("s_waitcnt vmcnt(" #n ")" ::: "memory")
; #define PG8_WAIT_L(n) asm volatile("s_waitcnt lgkmcnt(" #n ")" ::: "memory")
; #define PG8_BAR __builtin_amdgcn_s_barrier()
; #define PG8_SCHED __builtin_amdgcn_sched_barrier(0)
; template <class Epi, class Sched, bool ALIGN_EPI = false, bool SP2 = false>
; __device__ __forceinline__ void gemm_phase(PG8_LAS unsigned char* lds, const Gemm g, const Sched& S, const Epi& E, int wid0) {
;     ...
;             const bool last = (t == nt - 2);
;             const char* a1 = cA + (size_t)(t + 1) * kstep;
;             const char* a2 = last ? nA : cA + (size_t)(t + 2) * kstep; const char* b2 = last ? nB : cB + (size_t)(t + 2) * kstep;
;             const char* a3 = a2 + kstep; const char* b3 = b2 + kstep;
;             if (last && has_next) S.a_ready(nxt);
;             if constexpr (SP2) {
;             PG8_LDB(B0, 0, 0); PG8_LDB(B1, 0, 1); PG8_SCHED; PG8_LDA(At, 0, 0); PG8_STAGE(PG8_SA(1, 1), a1 + hstep, voffA);
;             PG8_WAIT_V(8); PG8_WAIT_L(0); PG8_BAR; PG8_MMA(0, 0, At, B0); PG8_MMA(0, 1, At, B1); PG8_BAR; PG8_SCHED;
;             PG8_LDA(At, 0, 1); PG8_STAGE(PG8_SB(0, 0), b2, voffB); PG8_STAGE(PG8_SB(0, 1), b2 + hstep, voffB); PG8_STAGE(PG8_SA(0, 0), a2, voffA);
.LBB0_167:
	s_add_i32 s65, 0, 0x10000
	s_add_i32 s66, 0, 0x14000
	v_add_u32_e32 v108, s65, v161
	v_add_u32_e32 v158, s66, v161
	ds_read_b128 v[96:99], v108
	ds_read_b128 v[100:103], v108 offset:1024
	ds_read_b128 v[104:107], v108 offset:2048
	ds_read_b128 v[108:111], v108 offset:3072
	ds_read_b128 v[154:157], v158
	ds_read_b128 v[164:167], v158 offset:1024
	ds_read_b128 v[168:171], v158 offset:2048
	ds_read_b128 v[172:175], v158 offset:3072
	v_lshl_add_u64 v[158:159], s[82:83], 0, v[152:153]
	s_add_i32 m0, s7, 0xc000
	ds_read_b128 v[176:179], v163
	ds_read_b128 v[180:183], v163 offset:1024
	ds_read_b128 v[184:187], v163 offset:2048
	ds_read_b128 v[188:191], v163 offset:3072
	ds_read_b128 v[198:201], v163 offset:4096
	ds_read_b128 v[202:205], v163 offset:5120
	ds_read_b128 v[206:209], v163 offset:6144
	ds_read_b128 v[210:213], v163 offset:7168
	global_load_lds_dwordx4 v[158:159], off
	v_lshl_add_u64 v[158:159], s[82:83], 0, v[150:151]
	s_add_i32 m0, s7, 0xe000
	s_nop 0
	global_load_lds_dwordx4 v[158:159], off
	s_add_u32 s26, s82, 0xfffc0080
	s_addc_u32 s27, s83, -1
	s_cmp_eq_u32 s64, 12
	s_cselect_b32 s87, s75, s27
	s_cselect_b32 s86, s94, s26
	s_cselect_b32 s85, s73, s11
	s_cselect_b32 s84, s95, s10
	s_waitcnt vmcnt(8)
	s_waitcnt lgkmcnt(0)
	s_barrier
	s_setprio 1
	v_mfma_f32_16x16x32_bf16 v[140:143], v[96:99], v[176:179], v[140:143]
	v_mfma_f32_16x16x32_bf16 v[136:139], v[104:107], v[176:179], v[136:139]
	v_mfma_f32_16x16x32_bf16 v[124:127], v[96:99], v[184:187], v[124:127]
	v_mfma_f32_16x16x32_bf16 v[120:123], v[104:107], v[184:187], v[120:123]
	v_mfma_f32_16x16x32_bf16 v[92:95], v[96:99], v[198:201], v[92:95]
	v_mfma_f32_16x16x32_bf16 v[88:91], v[104:107], v[198:201], v[88:91]
	v_mfma_f32_16x16x32_bf16 v[76:79], v[96:99], v[206:209], v[76:79]
	v_mfma_f32_16x16x32_bf16 v[72:75], v[104:107], v[206:209], v[72:75]
	v_mfma_f32_16x16x32_bf16 v[140:143], v[100:103], v[180:183], v[140:143]
	v_mfma_f32_16x16x32_bf16 v[136:139], v[108:111], v[180:183], v[136:139]
	v_mfma_f32_16x16x32_bf16 v[124:127], v[100:103], v[188:191], v[124:127]
	v_mfma_f32_16x16x32_bf16 v[120:123], v[108:111], v[188:191], v[120:123]
	v_mfma_f32_16x16x32_bf16 v[92:95], v[100:103], v[202:205], v[92:95]
	v_mfma_f32_16x16x32_bf16 v[88:91], v[108:111], v[202:205], v[88:91]
	v_mfma_f32_16x16x32_bf16 v[76:79], v[100:103], v[210:213], v[76:79]
	v_mfma_f32_16x16x32_bf16 v[72:75], v[108:111], v[210:213], v[72:75]
	s_setprio 0
	s_setprio 1
	v_mfma_f32_16x16x32_bf16 v[132:135], v[154:157], v[176:179], v[132:135]
	v_mfma_f32_16x16x32_bf16 v[128:131], v[168:171], v[176:179], v[128:131]
	v_mfma_f32_16x16x32_bf16 v[116:119], v[154:157], v[184:187], v[116:119]
	v_mfma_f32_16x16x32_bf16 v[112:115], v[168:171], v[184:187], v[112:115]
	v_mfma_f32_16x16x32_bf16 v[84:87], v[154:157], v[198:201], v[84:87]
	v_mfma_f32_16x16x32_bf16 v[80:83], v[168:171], v[198:201], v[80:83]
	v_mfma_f32_16x16x32_bf16 v[68:71], v[154:157], v[206:209], v[68:71]
	v_mfma_f32_16x16x32_bf16 v[64:67], v[168:171], v[206:209], v[64:67]
	v_mfma_f32_16x16x32_bf16 v[132:135], v[164:167], v[180:183], v[132:135]
	v_mfma_f32_16x16x32_bf16 v[128:131], v[172:175], v[180:183], v[128:131]
	v_mfma_f32_16x16x32_bf16 v[116:119], v[164:167], v[188:191], v[116:119]
	v_mfma_f32_16x16x32_bf16 v[112:115], v[172:175], v[188:191], v[112:115]
	v_mfma_f32_16x16x32_bf16 v[84:87], v[164:167], v[202:205], v[84:87]
	v_mfma_f32_16x16x32_bf16 v[80:83], v[172:175], v[202:205], v[80:83]
	v_mfma_f32_16x16x32_bf16 v[68:71], v[164:167], v[210:213], v[68:71]
	v_mfma_f32_16x16x32_bf16 v[64:67], v[172:175], v[210:213], v[64:67]
	s_barrier
	s_setprio 0
	s_add_i32 s26, s65, s6
	v_lshl_add_u64 v[158:159], s[84:85], 0, v[192:193]
	s_mov_b32 m0, s26
	ds_read_b128 v[176:179], v163 offset:16384
	ds_read_b128 v[180:183], v163 offset:17408
	ds_read_b128 v[184:187], v163 offset:18432
	ds_read_b128 v[188:191], v163 offset:19456
	ds_read_b128 v[198:201], v163 offset:20480
	ds_read_b128 v[202:205], v163 offset:21504
	ds_read_b128 v[206:209], v163 offset:22528
	ds_read_b128 v[210:213], v163 offset:23552
	global_load_lds_dwordx4 v[158:159], off
	s_add_i32 m0, s26, 0x2000
	s_add_u32 s26, s84, 0x40000
	v_lshl_add_u64 v[194:195], s[84:85], 0, v[144:145]
	s_addc_u32 s27, s85, 0
	s_add_i32 s65, s66, s6
	global_load_lds_dwordx4 v[194:195], off
	v_lshl_add_u64 v[196:197], s[26:27], 0, v[192:193]
	s_mov_b32 m0, s65
	v_lshl_add_u64 v[214:215], s[86:87], 0, v[146:147]
	global_load_lds_dwordx4 v[196:197], off
	v_lshl_add_u64 v[196:197], s[26:27], 0, v[144:145]
	s_add_i32 m0, s65, 0x2000
	s_nop 0
	global_load_lds_dwordx4 v[196:197], off
	v_lshl_add_u64 v[196:197], s[86:87], 0, v[148:149]
	s_mov_b32 m0, s7
	s_nop 0
	global_load_lds_dwordx4 v[196:197], off
	s_mov_b32 m0, s44
	s_nop 0
	global_load_lds_dwordx4 v[214:215], off
	s_waitcnt vmcnt(8)
	s_waitcnt lgkmcnt(0)
	s_barrier
; #define PG8_STAGE(bufoff, gbase, voff) do { _Pragma("unroll") for (int _i = 0; _i < 2; ++_i) \
;         __builtin_amdgcn_global_load_lds((const unsigned*)((const char*)(gbase) + (voff)[_i]), (PG8_LAS unsigned*)(lds + (bufoff) + ldsw + _i * 8192), 16, 0, 0); } while (0)
; #define PG8_LDA(dst, b, h) do { _Pragma("unroll") for (int m = 0; m < 4; ++m) _Pragma("unroll") for (int k = 0; k < 2; ++k) dst[m][k] = *(const PG8_LAS bf16x8*)(lds + PG8_SA(b, h) + aoff + m * 2048 + k * 1024); } while (0)
; #define PG8_LDB(dst, b, h) do { _Pragma("unroll") for (int n = 0; n < 2; ++n) _Pragma("unroll") for (int k = 0; k < 2; ++k) dst[n][k] = *(const PG8_LAS bf16x8*)(lds + PG8_SB(b, h) + boff + n * 2048 + k * 1024); } while (0)
; #define PG8_MMA(ai, bj, At, Bt) do { __builtin_amdgcn_s_setprio(1); _Pragma("unroll") for (int m = 0; m < 4; ++m) _Pragma("unroll") for (int n = 0; n < 2; ++n) _Pragma("unroll") for (int k = 0; k < 2; ++k) \
;         acc[ai][bj][m][n] = __builtin_amdgcn_mfma_f32_16x16x32_bf16(Bt[n][k], At[m][k], acc[ai][bj][m][n], 0, 0, 0); __builtin_amdgcn_s_setprio(0); } while (0)
; #define PG8_WAIT_V(n) asm volatile("s_waitcnt vmcnt(" #n ")" ::: "memory")
; #define PG8_WAIT_L(n) asm volatile("s_waitcnt lgkmcnt(" #n ")" ::: "memory")
; #define PG8_BAR __builtin_amdgcn_s_barrier()
; #define PG8_SCHED __builtin_amdgcn_sched_barrier(0)
; template <class Epi, class Sched, bool ALIGN_EPI = false, bool SP2 = false>
; __device__ __forceinline__ void gemm_phase(PG8_LAS unsigned char* lds, const Gemm g, const Sched& S, const Epi& E, int wid0) {
;     ...
;             PG8_WAIT_V(8); PG8_WAIT_L(0); PG8_BAR; PG8_MMA(1, 0, At, B0); PG8_MMA(1, 1, At, B1); PG8_BAR; PG8_SCHED;
;             PG8_LDB(B0, 1, 0); PG8_LDB(B1, 1, 1); PG8_SCHED; PG8_LDA(At, 1, 0); PG8_STAGE(PG8_SA(0, 1), a2 + hstep, voffA);
;             PG8_WAIT_V(8); PG8_WAIT_L(0); PG8_BAR; PG8_MMA(0, 0, At, B0); PG8_MMA(0, 1, At, B1); PG8_BAR; PG8_SCHED;
	s_setprio 1
	v_mfma_f32_16x16x32_bf16 v[60:63], v[96:99], v[176:179], v[60:63]
	v_mfma_f32_16x16x32_bf16 v[56:59], v[104:107], v[176:179], v[56:59]
	v_mfma_f32_16x16x32_bf16 v[48:51], v[96:99], v[184:187], v[48:51]
	v_mfma_f32_16x16x32_bf16 v[40:43], v[104:107], v[184:187], v[40:43]
	v_mfma_f32_16x16x32_bf16 v[32:35], v[96:99], v[198:201], v[32:35]
	v_mfma_f32_16x16x32_bf16 v[24:27], v[104:107], v[198:201], v[24:27]
	v_mfma_f32_16x16x32_bf16 v[16:19], v[96:99], v[206:209], v[16:19]
	v_mfma_f32_16x16x32_bf16 v[8:11], v[104:107], v[206:209], v[8:11]
	v_mfma_f32_16x16x32_bf16 v[60:63], v[100:103], v[180:183], v[60:63]
	v_mfma_f32_16x16x32_bf16 v[56:59], v[108:111], v[180:183], v[56:59]
	v_mfma_f32_16x16x32_bf16 v[48:51], v[100:103], v[188:191], v[48:51]
	v_mfma_f32_16x16x32_bf16 v[40:43], v[108:111], v[188:191], v[40:43]
	v_mfma_f32_16x16x32_bf16 v[32:35], v[100:103], v[202:205], v[32:35]
	v_mfma_f32_16x16x32_bf16 v[24:27], v[108:111], v[202:205], v[24:27]
	v_mfma_f32_16x16x32_bf16 v[16:19], v[100:103], v[210:213], v[16:19]
	v_mfma_f32_16x16x32_bf16 v[8:11], v[108:111], v[210:213], v[8:11]
	s_setprio 0
	s_setprio 1
	v_mfma_f32_16x16x32_bf16 v[52:55], v[154:157], v[176:179], v[52:55]
	v_mfma_f32_16x16x32_bf16 v[44:47], v[168:171], v[176:179], v[44:47]
	v_mfma_f32_16x16x32_bf16 v[36:39], v[154:157], v[184:187], v[36:39]
	v_mfma_f32_16x16x32_bf16 v[28:31], v[168:171], v[184:187], v[28:31]
	v_mfma_f32_16x16x32_bf16 v[20:23], v[154:157], v[198:201], v[20:23]
	v_mfma_f32_16x16x32_bf16 v[12:15], v[168:171], v[198:201], v[12:15]
	v_mfma_f32_16x16x32_bf16 v[4:7], v[154:157], v[206:209], v[4:7]
	v_mfma_f32_16x16x32_bf16 v[0:3], v[168:171], v[206:209], v[0:3]
	v_mfma_f32_16x16x32_bf16 v[52:55], v[164:167], v[180:183], v[52:55]
	v_mfma_f32_16x16x32_bf16 v[44:47], v[172:175], v[180:183], v[44:47]
	v_mfma_f32_16x16x32_bf16 v[36:39], v[164:167], v[188:191], v[36:39]
	v_mfma_f32_16x16x32_bf16 v[28:31], v[172:175], v[188:191], v[28:31]
	v_mfma_f32_16x16x32_bf16 v[20:23], v[164:167], v[202:205], v[20:23]
	v_mfma_f32_16x16x32_bf16 v[12:15], v[172:175], v[202:205], v[12:15]
	v_mfma_f32_16x16x32_bf16 v[4:7], v[164:167], v[210:213], v[4:7]
	v_mfma_f32_16x16x32_bf16 v[0:3], v[172:175], v[210:213], v[0:3]
	s_barrier
	s_setprio 0
	s_add_i32 s65, 0, 0x18000
	s_add_i32 s66, 0, 0x1c000
	v_add_u32_e32 v108, s65, v161
	v_add_u32_e32 v172, s66, v161
	ds_read_b128 v[96:99], v108
	ds_read_b128 v[100:103], v108 offset:1024
	ds_read_b128 v[104:107], v108 offset:2048
	ds_read_b128 v[108:111], v108 offset:3072
	ds_read_b128 v[154:157], v172
	ds_read_b128 v[164:167], v172 offset:1024
	ds_read_b128 v[168:171], v172 offset:2048
	ds_read_b128 v[172:175], v172 offset:3072
	s_add_u32 s26, s86, 0x40000
	s_addc_u32 s27, s87, 0
	s_mov_b32 m0, s45
	v_lshl_add_u64 v[220:221], s[26:27], 0, v[148:149]
	ds_read_b128 v[176:179], v163 offset:32768
	ds_read_b128 v[180:183], v163 offset:33792
	ds_read_b128 v[184:187], v163 offset:34816
	ds_read_b128 v[188:191], v163 offset:35840
	ds_read_b128 v[198:201], v163 offset:36864
	ds_read_b128 v[202:205], v163 offset:37888
	ds_read_b128 v[206:209], v163 offset:38912
	ds_read_b128 v[210:213], v163 offset:39936
	global_load_lds_dwordx4 v[220:221], off
	v_lshl_add_u64 v[220:221], s[26:27], 0, v[146:147]
	s_mov_b32 m0, s91
	s_nop 0
	global_load_lds_dwordx4 v[220:221], off
	s_waitcnt vmcnt(8)
	s_waitcnt lgkmcnt(0)
	s_barrier
	s_setprio 1
	v_mfma_f32_16x16x32_bf16 v[140:143], v[96:99], v[176:179], v[140:143]
	v_mfma_f32_16x16x32_bf16 v[136:139], v[104:107], v[176:179], v[136:139]
	v_mfma_f32_16x16x32_bf16 v[124:127], v[96:99], v[184:187], v[124:127]
	v_mfma_f32_16x16x32_bf16 v[120:123], v[104:107], v[184:187], v[120:123]
	v_mfma_f32_16x16x32_bf16 v[92:95], v[96:99], v[198:201], v[92:95]
	v_mfma_f32_16x16x32_bf16 v[88:91], v[104:107], v[198:201], v[88:91]
	v_mfma_f32_16x16x32_bf16 v[76:79], v[96:99], v[206:209], v[76:79]
	v_mfma_f32_16x16x32_bf16 v[72:75], v[104:107], v[206:209], v[72:75]
	v_mfma_f32_16x16x32_bf16 v[140:143], v[100:103], v[180:183], v[140:143]
	v_mfma_f32_16x16x32_bf16 v[136:139], v[108:111], v[180:183], v[136:139]
	v_mfma_f32_16x16x32_bf16 v[124:127], v[100:103], v[188:191], v[124:127]
	v_mfma_f32_16x16x32_bf16 v[120:123], v[108:111], v[188:191], v[120:123]
	v_mfma_f32_16x16x32_bf16 v[92:95], v[100:103], v[202:205], v[92:95]
	v_mfma_f32_16x16x32_bf16 v[88:91], v[108:111], v[202:205], v[88:91]
	v_mfma_f32_16x16x32_bf16 v[76:79], v[100:103], v[210:213], v[76:79]
	v_mfma_f32_16x16x32_bf16 v[72:75], v[108:111], v[210:213], v[72:75]
	s_setprio 0
	s_setprio 1
	v_mfma_f32_16x16x32_bf16 v[132:135], v[154:157], v[176:179], v[132:135]
	v_mfma_f32_16x16x32_bf16 v[128:131], v[168:171], v[176:179], v[128:131]
	v_mfma_f32_16x16x32_bf16 v[116:119], v[154:157], v[184:187], v[116:119]
	v_mfma_f32_16x16x32_bf16 v[112:115], v[168:171], v[184:187], v[112:115]
	v_mfma_f32_16x16x32_bf16 v[84:87], v[154:157], v[198:201], v[84:87]
	v_mfma_f32_16x16x32_bf16 v[80:83], v[168:171], v[198:201], v[80:83]
	v_mfma_f32_16x16x32_bf16 v[68:71], v[154:157], v[206:209], v[68:71]
	v_mfma_f32_16x16x32_bf16 v[64:67], v[168:171], v[206:209], v[64:67]
	v_mfma_f32_16x16x32_bf16 v[132:135], v[164:167], v[180:183], v[132:135]
	v_mfma_f32_16x16x32_bf16 v[128:131], v[172:175], v[180:183], v[128:131]
	v_mfma_f32_16x16x32_bf16 v[116:119], v[164:167], v[188:191], v[116:119]
	v_mfma_f32_16x16x32_bf16 v[112:115], v[172:175], v[188:191], v[112:115]
	v_mfma_f32_16x16x32_bf16 v[84:87], v[164:167], v[202:205], v[84:87]
	v_mfma_f32_16x16x32_bf16 v[80:83], v[172:175], v[202:205], v[80:83]
	v_mfma_f32_16x16x32_bf16 v[68:71], v[164:167], v[210:213], v[68:71]
	v_mfma_f32_16x16x32_bf16 v[64:67], v[172:175], v[210:213], v[64:67]
	s_barrier
; #define PG8_STAGE(bufoff, gbase, voff) do { _Pragma("unroll") for (int _i = 0; _i < 2; ++_i) \
;         __builtin_amdgcn_global_load_lds((const unsigned*)((const char*)(gbase) + (voff)[_i]), (PG8_LAS unsigned*)(lds + (bufoff) + ldsw + _i * 8192), 16, 0, 0); } while (0)
; #define PG8_LDA(dst, b, h) do { _Pragma("unroll") for (int m = 0; m < 4; ++m) _Pragma("unroll") for (int k = 0; k < 2; ++k) dst[m][k] = *(const PG8_LAS bf16x8*)(lds + PG8_SA(b, h) + aoff + m * 2048 + k * 1024); } while (0)
; #define PG8_MMA(ai, bj, At, Bt) do { __builtin_amdgcn_s_setprio(1); _Pragma("unroll") for (int m = 0; m < 4; ++m) _Pragma("unroll") for (int n = 0; n < 2; ++n) _Pragma("unroll") for (int k = 0; k < 2; ++k) \
;         acc[ai][bj][m][n] = __builtin_amdgcn_mfma_f32_16x16x32_bf16(Bt[n][k], At[m][k], acc[ai][bj][m][n], 0, 0, 0); __builtin_amdgcn_s_setprio(0); } while (0)
; #define PG8_WAIT_V(n) asm volatile("s_waitcnt vmcnt(" #n ")" ::: "memory")
; #define PG8_WAIT_L(n) asm volatile("s_waitcnt lgkmcnt(" #n ")" ::: "memory")
; #define PG8_BAR __builtin_amdgcn_s_barrier()
; #define PG8_SCHED __builtin_amdgcn_sched_barrier(0)
; template <class Epi, class Sched, bool ALIGN_EPI = false, bool SP2 = false>
; __device__ __forceinline__ void gemm_phase(PG8_LAS unsigned char* lds, const Gemm g, const Sched& S, const Epi& E, int wid0) {
;     ...
;             PG8_LDA(At, 1, 1); PG8_STAGE(PG8_SB(1, 0), b3, voffB); PG8_STAGE(PG8_SB(1, 1), b3 + hstep, voffB); PG8_STAGE(PG8_SA(1, 0), a3, voffA);
;             PG8_WAIT_V(8); PG8_WAIT_L(0); PG8_BAR; PG8_MMA(1, 0, At, B0); PG8_MMA(1, 1, At, B1); PG8_BAR; PG8_SCHED;
;     ...
;         if constexpr (ALIGN_EPI) { if (wr == 0) PG8_BAR; }
	s_setprio 0
	s_add_i32 s26, s65, s6
	v_lshl_add_u64 v[158:159], v[158:159], 0, s[30:31]
	s_mov_b32 m0, s26
	ds_read_b128 v[176:179], v163 offset:49152
	ds_read_b128 v[180:183], v163 offset:50176
	ds_read_b128 v[184:187], v163 offset:51200
	ds_read_b128 v[188:191], v163 offset:52224
	ds_read_b128 v[198:201], v163 offset:53248
	ds_read_b128 v[202:205], v163 offset:54272
	ds_read_b128 v[206:209], v163 offset:55296
	ds_read_b128 v[210:213], v163 offset:56320
	global_load_lds_dwordx4 v[158:159], off
	s_add_i32 m0, s26, 0x2000
	s_add_u32 s26, s84, 0x40080
	v_lshl_add_u64 v[158:159], v[194:195], 0, s[30:31]
	s_addc_u32 s27, s85, 0
	s_add_i32 s65, s66, s6
	global_load_lds_dwordx4 v[158:159], off
	v_lshl_add_u64 v[158:159], s[26:27], 0, v[192:193]
	s_mov_b32 m0, s65
	s_nop 0
	global_load_lds_dwordx4 v[158:159], off
	v_lshl_add_u64 v[158:159], s[26:27], 0, v[144:145]
	s_add_i32 m0, s65, 0x2000
	s_nop 0
	global_load_lds_dwordx4 v[158:159], off
	v_lshl_add_u64 v[158:159], v[196:197], 0, s[30:31]
	s_mov_b32 m0, s22
	s_nop 0
	global_load_lds_dwordx4 v[158:159], off
	v_lshl_add_u64 v[158:159], v[214:215], 0, s[30:31]
	s_mov_b32 m0, s92
	s_nop 0
	global_load_lds_dwordx4 v[158:159], off
	s_waitcnt vmcnt(8)
	s_waitcnt lgkmcnt(0)
	s_barrier
	s_setprio 1
	v_mfma_f32_16x16x32_bf16 v[60:63], v[96:99], v[176:179], v[60:63]
	v_mfma_f32_16x16x32_bf16 v[56:59], v[104:107], v[176:179], v[56:59]
	v_mfma_f32_16x16x32_bf16 v[48:51], v[96:99], v[184:187], v[48:51]
	v_mfma_f32_16x16x32_bf16 v[40:43], v[104:107], v[184:187], v[40:43]
	v_mfma_f32_16x16x32_bf16 v[32:35], v[96:99], v[198:201], v[32:35]
	v_mfma_f32_16x16x32_bf16 v[24:27], v[104:107], v[198:201], v[24:27]
	v_mfma_f32_16x16x32_bf16 v[16:19], v[96:99], v[206:209], v[16:19]
	v_mfma_f32_16x16x32_bf16 v[8:11], v[104:107], v[206:209], v[8:11]
	v_mfma_f32_16x16x32_bf16 v[60:63], v[100:103], v[180:183], v[60:63]
	v_mfma_f32_16x16x32_bf16 v[56:59], v[108:111], v[180:183], v[56:59]
	v_mfma_f32_16x16x32_bf16 v[48:51], v[100:103], v[188:191], v[48:51]
	v_mfma_f32_16x16x32_bf16 v[40:43], v[108:111], v[188:191], v[40:43]
	v_mfma_f32_16x16x32_bf16 v[32:35], v[100:103], v[202:205], v[32:35]
	v_mfma_f32_16x16x32_bf16 v[24:27], v[108:111], v[202:205], v[24:27]
	v_mfma_f32_16x16x32_bf16 v[16:19], v[100:103], v[210:213], v[16:19]
	v_mfma_f32_16x16x32_bf16 v[8:11], v[108:111], v[210:213], v[8:11]
	s_setprio 0
	s_setprio 1
	v_mfma_f32_16x16x32_bf16 v[52:55], v[154:157], v[176:179], v[52:55]
	v_mfma_f32_16x16x32_bf16 v[44:47], v[168:171], v[176:179], v[44:47]
	v_mfma_f32_16x16x32_bf16 v[36:39], v[154:157], v[184:187], v[36:39]
	v_mfma_f32_16x16x32_bf16 v[28:31], v[168:171], v[184:187], v[28:31]
	v_mfma_f32_16x16x32_bf16 v[20:23], v[154:157], v[198:201], v[20:23]
	v_mfma_f32_16x16x32_bf16 v[12:15], v[168:171], v[198:201], v[12:15]
	v_mfma_f32_16x16x32_bf16 v[4:7], v[154:157], v[206:209], v[4:7]
	v_mfma_f32_16x16x32_bf16 v[0:3], v[168:171], v[206:209], v[0:3]
	v_mfma_f32_16x16x32_bf16 v[52:55], v[164:167], v[180:183], v[52:55]
	v_mfma_f32_16x16x32_bf16 v[44:47], v[172:175], v[180:183], v[44:47]
	v_mfma_f32_16x16x32_bf16 v[36:39], v[164:167], v[188:191], v[36:39]
	v_mfma_f32_16x16x32_bf16 v[28:31], v[172:175], v[188:191], v[28:31]
	v_mfma_f32_16x16x32_bf16 v[20:23], v[164:167], v[202:205], v[20:23]
	v_mfma_f32_16x16x32_bf16 v[12:15], v[172:175], v[202:205], v[12:15]
	v_mfma_f32_16x16x32_bf16 v[4:7], v[164:167], v[210:213], v[4:7]
	v_mfma_f32_16x16x32_bf16 v[0:3], v[172:175], v[210:213], v[0:3]
	s_barrier
	s_setprio 0
	s_add_i32 s64, s64, 2
	s_add_u32 s10, s10, 0x100
	s_addc_u32 s11, s11, 0
	s_add_u32 s82, s82, 0x100
	s_addc_u32 s83, s83, 0
	s_cmp_gt_u32 s64, 13
	s_cbranch_scc0 .LBB0_167
	s_and_b64 vcc, exec, s[70:71]
	s_cbranch_vccz .LBB0_170
	s_barrier

; #define PG8_STAGE(bufoff, gbase, voff) do { _Pragma("unroll") for (int _i = 0; _i < 2; ++_i) \
;         __builtin_amdgcn_global_load_lds((const unsigned*)((const char*)(gbase) + (voff)[_i]), (PG8_LAS unsigned*)(lds + (bufoff) + ldsw + _i * 8192), 16, 0, 0); } while (0)
; #define PG8_LDA(dst, b, h) do { _Pragma("unroll") for (int m = 0; m < 4; ++m) _Pragma("unroll") for (int k = 0; k < 2; ++k) dst[m][k] = *(const PG8_LAS bf16x8*)(lds + PG8_SA(b, h) + aoff + m * 2048 + k * 1024); } while (0)
; #define PG8_LDB(dst, b, h) do { _Pragma("unroll") for (int n = 0; n < 2; ++n) _Pragma("unroll") for (int k = 0; k < 2; ++k) dst[n][k] = *(const PG8_LAS bf16x8*)(lds + PG8_SB(b, h) + boff + n * 2048 + k * 1024); } while (0)
; #define PG8_MMA(ai, bj, At, Bt) do { __builtin_amdgcn_s_setprio(1); _Pragma("unroll") for (int m = 0; m < 4; ++m) _Pragma("unroll") for (int n = 0; n < 2; ++n) _Pragma("unroll") for (int k = 0; k < 2; ++k) \
;         acc[ai][bj][m][n] = __builtin_amdgcn_mfma_f32_16x16x32_bf16(Bt[n][k], At[m][k], acc[ai][bj][m][n], 0, 0, 0); __builtin_amdgcn_s_setprio(0); } while (0)
; #define PG8_WAIT_V(n) asm volatile("s_waitcnt vmcnt(" #n ")" ::: "memory")
; #define PG8_WAIT_L(n) asm volatile("s_waitcnt lgkmcnt(" #n ")" ::: "memory")
; #define PG8_BAR __builtin_amdgcn_s_barrier()
; #define PG8_SCHED __builtin_amdgcn_sched_barrier(0)
; template <class Epi, class Sched, bool ALIGN_EPI = false, bool SP2 = false>
; __device__ __forceinline__ void gemm_phase(PG8_LAS unsigned char* lds, const Gemm g, const Sched& S, const Epi& E, int wid0) {
;     ...
;             const bool last = (t == nt - 2);
;             const char* a1 = cA + (size_t)(t + 1) * kstep;
;             const char* a2 = last ? nA : cA + (size_t)(t + 2) * kstep; const char* b2 = last ? nB : cB + (size_t)(t + 2) * kstep;
;             const char* a3 = a2 + kstep; const char* b3 = b2 + kstep;
;             if (last && has_next) S.a_ready(nxt);
;             if constexpr (SP2) {
;             PG8_LDB(B0, 0, 0); PG8_LDB(B1, 0, 1); PG8_SCHED; PG8_LDA(At, 0, 0); PG8_STAGE(PG8_SA(1, 1), a1 + hstep, voffA);
;             PG8_WAIT_V(8); PG8_WAIT_L(0); PG8_BAR; PG8_MMA(0, 0, At, B0); PG8_MMA(0, 1, At, B1); PG8_BAR; PG8_SCHED;
;             PG8_LDA(At, 0, 1); PG8_STAGE(PG8_SB(0, 0), b2, voffB); PG8_STAGE(PG8_SB(0, 1), b2 + hstep, voffB); PG8_STAGE(PG8_SA(0, 0), a2, voffA);
.LBB0_377:
	s_add_i32 s65, 0, 0x10000
	s_add_i32 s66, 0, 0x14000
	v_add_u32_e32 v156, s65, v143
	v_add_u32_e32 v172, s66, v143
	ds_read_b128 v[138:141], v156
	ds_read_b128 v[148:151], v156 offset:1024
	ds_read_b128 v[152:155], v156 offset:2048
	ds_read_b128 v[156:159], v156 offset:3072
	ds_read_b128 v[160:163], v172
	ds_read_b128 v[164:167], v172 offset:1024
	ds_read_b128 v[168:171], v172 offset:2048
	ds_read_b128 v[172:175], v172 offset:3072
	v_lshl_add_u64 v[210:211], s[84:85], 0, v[136:137]
	s_add_i32 m0, s83, 0xc000
	ds_read_b128 v[176:179], v147
	ds_read_b128 v[180:183], v147 offset:1024
	ds_read_b128 v[184:187], v147 offset:2048
	ds_read_b128 v[188:191], v147 offset:3072
	ds_read_b128 v[194:197], v147 offset:4096
	ds_read_b128 v[198:201], v147 offset:5120
	ds_read_b128 v[202:205], v147 offset:6144
	ds_read_b128 v[206:209], v147 offset:7168
	global_load_lds_dwordx4 v[210:211], off
	v_lshl_add_u64 v[210:211], s[84:85], 0, v[134:135]
	s_add_i32 m0, s83, 0xe000
	s_nop 0
	global_load_lds_dwordx4 v[210:211], off
	s_add_u32 s26, s84, 0xfffc0080
	s_addc_u32 s27, s85, -1
	s_cmp_eq_u32 s64, 12
	s_cselect_b32 vcc_hi, s22, s27
	s_cselect_b32 vcc_lo, s75, s26
	s_cselect_b32 s77, s73, s11
	s_cselect_b32 s76, s81, s10
	s_waitcnt vmcnt(8)
	s_waitcnt lgkmcnt(0)
	s_barrier
	s_setprio 1
	v_mfma_f32_16x16x32_bf16 v[124:127], v[138:141], v[176:179], v[124:127]
	v_mfma_f32_16x16x32_bf16 v[120:123], v[152:155], v[176:179], v[120:123]
	v_mfma_f32_16x16x32_bf16 v[108:111], v[138:141], v[184:187], v[108:111]
	v_mfma_f32_16x16x32_bf16 v[104:107], v[152:155], v[184:187], v[104:107]
	v_mfma_f32_16x16x32_bf16 v[92:95], v[138:141], v[194:197], v[92:95]
	v_mfma_f32_16x16x32_bf16 v[88:91], v[152:155], v[194:197], v[88:91]
	v_mfma_f32_16x16x32_bf16 v[76:79], v[138:141], v[202:205], v[76:79]
	v_mfma_f32_16x16x32_bf16 v[72:75], v[152:155], v[202:205], v[72:75]
	v_mfma_f32_16x16x32_bf16 v[124:127], v[148:151], v[180:183], v[124:127]
	v_mfma_f32_16x16x32_bf16 v[120:123], v[156:159], v[180:183], v[120:123]
	v_mfma_f32_16x16x32_bf16 v[108:111], v[148:151], v[188:191], v[108:111]
	v_mfma_f32_16x16x32_bf16 v[104:107], v[156:159], v[188:191], v[104:107]
	v_mfma_f32_16x16x32_bf16 v[92:95], v[148:151], v[198:201], v[92:95]
	v_mfma_f32_16x16x32_bf16 v[88:91], v[156:159], v[198:201], v[88:91]
	v_mfma_f32_16x16x32_bf16 v[76:79], v[148:151], v[206:209], v[76:79]
	v_mfma_f32_16x16x32_bf16 v[72:75], v[156:159], v[206:209], v[72:75]
	s_setprio 0
	s_setprio 1
	v_mfma_f32_16x16x32_bf16 v[116:119], v[160:163], v[176:179], v[116:119]
	v_mfma_f32_16x16x32_bf16 v[112:115], v[168:171], v[176:179], v[112:115]
	v_mfma_f32_16x16x32_bf16 v[100:103], v[160:163], v[184:187], v[100:103]
	v_mfma_f32_16x16x32_bf16 v[96:99], v[168:171], v[184:187], v[96:99]
	v_mfma_f32_16x16x32_bf16 v[84:87], v[160:163], v[194:197], v[84:87]
	v_mfma_f32_16x16x32_bf16 v[80:83], v[168:171], v[194:197], v[80:83]
	v_mfma_f32_16x16x32_bf16 v[68:71], v[160:163], v[202:205], v[68:71]
	v_mfma_f32_16x16x32_bf16 v[64:67], v[168:171], v[202:205], v[64:67]
	v_mfma_f32_16x16x32_bf16 v[116:119], v[164:167], v[180:183], v[116:119]
	v_mfma_f32_16x16x32_bf16 v[112:115], v[172:175], v[180:183], v[112:115]
	v_mfma_f32_16x16x32_bf16 v[100:103], v[164:167], v[188:191], v[100:103]
	v_mfma_f32_16x16x32_bf16 v[96:99], v[172:175], v[188:191], v[96:99]
	v_mfma_f32_16x16x32_bf16 v[84:87], v[164:167], v[198:201], v[84:87]
	v_mfma_f32_16x16x32_bf16 v[80:83], v[172:175], v[198:201], v[80:83]
	v_mfma_f32_16x16x32_bf16 v[68:71], v[164:167], v[206:209], v[68:71]
	v_mfma_f32_16x16x32_bf16 v[64:67], v[172:175], v[206:209], v[64:67]
	s_barrier
	s_setprio 0
	s_add_i32 s26, s65, s69
	v_lshl_add_u64 v[210:211], s[76:77], 0, v[192:193]
	s_mov_b32 m0, s26
	ds_read_b128 v[176:179], v147 offset:16384
	ds_read_b128 v[180:183], v147 offset:17408
	ds_read_b128 v[184:187], v147 offset:18432
	ds_read_b128 v[188:191], v147 offset:19456
	ds_read_b128 v[194:197], v147 offset:20480
	ds_read_b128 v[198:201], v147 offset:21504
	ds_read_b128 v[202:205], v147 offset:22528
	ds_read_b128 v[206:209], v147 offset:23552
	global_load_lds_dwordx4 v[210:211], off
	s_add_i32 m0, s26, 0x2000
	s_add_u32 s26, s76, 0x40000
	v_lshl_add_u64 v[212:213], s[76:77], 0, v[132:133]
	s_addc_u32 s27, s77, 0
	s_add_i32 s65, s66, s69
	global_load_lds_dwordx4 v[212:213], off
	v_lshl_add_u64 v[214:215], s[26:27], 0, v[192:193]
	s_mov_b32 m0, s65
	v_lshl_add_u64 v[220:221], vcc, 0, v[130:131]
	global_load_lds_dwordx4 v[214:215], off
	v_lshl_add_u64 v[214:215], s[26:27], 0, v[132:133]
	s_add_i32 m0, s65, 0x2000
	s_nop 0
	global_load_lds_dwordx4 v[214:215], off
	v_lshl_add_u64 v[214:215], vcc, 0, v[128:129]
	s_mov_b32 m0, s83
	s_nop 0
	global_load_lds_dwordx4 v[214:215], off
	s_mov_b32 m0, s88
	s_nop 0
	global_load_lds_dwordx4 v[220:221], off
	s_waitcnt vmcnt(8)
	s_waitcnt lgkmcnt(0)
	s_barrier
; #define PG8_STAGE(bufoff, gbase, voff) do { _Pragma("unroll") for (int _i = 0; _i < 2; ++_i) \
;         __builtin_amdgcn_global_load_lds((const unsigned*)((const char*)(gbase) + (voff)[_i]), (PG8_LAS unsigned*)(lds + (bufoff) + ldsw + _i * 8192), 16, 0, 0); } while (0)
; #define PG8_LDA(dst, b, h) do { _Pragma("unroll") for (int m = 0; m < 4; ++m) _Pragma("unroll") for (int k = 0; k < 2; ++k) dst[m][k] = *(const PG8_LAS bf16x8*)(lds + PG8_SA(b, h) + aoff + m * 2048 + k * 1024); } while (0)
; #define PG8_LDB(dst, b, h) do { _Pragma("unroll") for (int n = 0; n < 2; ++n) _Pragma("unroll") for (int k = 0; k < 2; ++k) dst[n][k] = *(const PG8_LAS bf16x8*)(lds + PG8_SB(b, h) + boff + n * 2048 + k * 1024); } while (0)
; #define PG8_MMA(ai, bj, At, Bt) do { __builtin_amdgcn_s_setprio(1); _Pragma("unroll") for (int m = 0; m < 4; ++m) _Pragma("unroll") for (int n = 0; n < 2; ++n) _Pragma("unroll") for (int k = 0; k < 2; ++k) \
;         acc[ai][bj][m][n] = __builtin_amdgcn_mfma_f32_16x16x32_bf16(Bt[n][k], At[m][k], acc[ai][bj][m][n], 0, 0, 0); __builtin_amdgcn_s_setprio(0); } while (0)
; #define PG8_WAIT_V(n) asm volatile("s_waitcnt vmcnt(" #n ")" ::: "memory")
; #define PG8_WAIT_L(n) asm volatile("s_waitcnt lgkmcnt(" #n ")" ::: "memory")
; #define PG8_BAR __builtin_amdgcn_s_barrier()
; #define PG8_SCHED __builtin_amdgcn_sched_barrier(0)
; template <class Epi, class Sched, bool ALIGN_EPI = false, bool SP2 = false>
; __device__ __forceinline__ void gemm_phase(PG8_LAS unsigned char* lds, const Gemm g, const Sched& S, const Epi& E, int wid0) {
;     ...
;             PG8_WAIT_V(8); PG8_WAIT_L(0); PG8_BAR; PG8_MMA(1, 0, At, B0); PG8_MMA(1, 1, At, B1); PG8_BAR; PG8_SCHED;
;             PG8_LDB(B0, 1, 0); PG8_LDB(B1, 1, 1); PG8_SCHED; PG8_LDA(At, 1, 0); PG8_STAGE(PG8_SA(0, 1), a2 + hstep, voffA);
;             PG8_WAIT_V(8); PG8_WAIT_L(0); PG8_BAR; PG8_MMA(0, 0, At, B0); PG8_MMA(0, 1, At, B1); PG8_BAR; PG8_SCHED;
	s_setprio 1
	v_mfma_f32_16x16x32_bf16 v[60:63], v[138:141], v[176:179], v[60:63]
	v_mfma_f32_16x16x32_bf16 v[56:59], v[152:155], v[176:179], v[56:59]
	v_mfma_f32_16x16x32_bf16 v[44:47], v[138:141], v[184:187], v[44:47]
	v_mfma_f32_16x16x32_bf16 v[40:43], v[152:155], v[184:187], v[40:43]
	v_mfma_f32_16x16x32_bf16 v[28:31], v[138:141], v[194:197], v[28:31]
	v_mfma_f32_16x16x32_bf16 v[24:27], v[152:155], v[194:197], v[24:27]
	v_mfma_f32_16x16x32_bf16 v[12:15], v[138:141], v[202:205], v[12:15]
	v_mfma_f32_16x16x32_bf16 v[8:11], v[152:155], v[202:205], v[8:11]
	v_mfma_f32_16x16x32_bf16 v[60:63], v[148:151], v[180:183], v[60:63]
	v_mfma_f32_16x16x32_bf16 v[56:59], v[156:159], v[180:183], v[56:59]
	v_mfma_f32_16x16x32_bf16 v[44:47], v[148:151], v[188:191], v[44:47]
	v_mfma_f32_16x16x32_bf16 v[40:43], v[156:159], v[188:191], v[40:43]
	v_mfma_f32_16x16x32_bf16 v[28:31], v[148:151], v[198:201], v[28:31]
	v_mfma_f32_16x16x32_bf16 v[24:27], v[156:159], v[198:201], v[24:27]
	v_mfma_f32_16x16x32_bf16 v[12:15], v[148:151], v[206:209], v[12:15]
	v_mfma_f32_16x16x32_bf16 v[8:11], v[156:159], v[206:209], v[8:11]
	s_setprio 0
	s_setprio 1
	v_mfma_f32_16x16x32_bf16 v[52:55], v[160:163], v[176:179], v[52:55]
	v_mfma_f32_16x16x32_bf16 v[48:51], v[168:171], v[176:179], v[48:51]
	v_mfma_f32_16x16x32_bf16 v[36:39], v[160:163], v[184:187], v[36:39]
	v_mfma_f32_16x16x32_bf16 v[32:35], v[168:171], v[184:187], v[32:35]
	v_mfma_f32_16x16x32_bf16 v[20:23], v[160:163], v[194:197], v[20:23]
	v_mfma_f32_16x16x32_bf16 v[16:19], v[168:171], v[194:197], v[16:19]
	v_mfma_f32_16x16x32_bf16 v[4:7], v[160:163], v[202:205], v[4:7]
	v_mfma_f32_16x16x32_bf16 v[0:3], v[168:171], v[202:205], v[0:3]
	v_mfma_f32_16x16x32_bf16 v[52:55], v[164:167], v[180:183], v[52:55]
	v_mfma_f32_16x16x32_bf16 v[48:51], v[172:175], v[180:183], v[48:51]
	v_mfma_f32_16x16x32_bf16 v[36:39], v[164:167], v[188:191], v[36:39]
	v_mfma_f32_16x16x32_bf16 v[32:35], v[172:175], v[188:191], v[32:35]
	v_mfma_f32_16x16x32_bf16 v[20:23], v[164:167], v[198:201], v[20:23]
	v_mfma_f32_16x16x32_bf16 v[16:19], v[172:175], v[198:201], v[16:19]
	v_mfma_f32_16x16x32_bf16 v[4:7], v[164:167], v[206:209], v[4:7]
	v_mfma_f32_16x16x32_bf16 v[0:3], v[172:175], v[206:209], v[0:3]
	s_barrier
	s_setprio 0
	s_add_i32 s65, 0, 0x18000
	s_add_i32 s66, 0, 0x1c000
	v_add_u32_e32 v156, s65, v143
	v_add_u32_e32 v172, s66, v143
	ds_read_b128 v[138:141], v156
	ds_read_b128 v[148:151], v156 offset:1024
	ds_read_b128 v[152:155], v156 offset:2048
	ds_read_b128 v[156:159], v156 offset:3072
	ds_read_b128 v[160:163], v172
	ds_read_b128 v[164:167], v172 offset:1024
	ds_read_b128 v[168:171], v172 offset:2048
	ds_read_b128 v[172:175], v172 offset:3072
	s_add_u32 s26, vcc_lo, 0x40000
	s_addc_u32 s27, vcc_hi, 0
	s_mov_b32 m0, s89
	v_lshl_add_u64 v[222:223], s[26:27], 0, v[128:129]
	ds_read_b128 v[176:179], v147 offset:32768
	ds_read_b128 v[180:183], v147 offset:33792
	ds_read_b128 v[184:187], v147 offset:34816
	ds_read_b128 v[188:191], v147 offset:35840
	ds_read_b128 v[194:197], v147 offset:36864
	ds_read_b128 v[198:201], v147 offset:37888
	ds_read_b128 v[202:205], v147 offset:38912
	ds_read_b128 v[206:209], v147 offset:39936
	global_load_lds_dwordx4 v[222:223], off
	v_lshl_add_u64 v[222:223], s[26:27], 0, v[130:131]
	s_mov_b32 m0, s90
	s_nop 0
	global_load_lds_dwordx4 v[222:223], off
	s_waitcnt vmcnt(8)
	s_waitcnt lgkmcnt(0)
	s_barrier
	s_setprio 1
	v_mfma_f32_16x16x32_bf16 v[124:127], v[138:141], v[176:179], v[124:127]
	v_mfma_f32_16x16x32_bf16 v[120:123], v[152:155], v[176:179], v[120:123]
	v_mfma_f32_16x16x32_bf16 v[108:111], v[138:141], v[184:187], v[108:111]
	v_mfma_f32_16x16x32_bf16 v[104:107], v[152:155], v[184:187], v[104:107]
	v_mfma_f32_16x16x32_bf16 v[92:95], v[138:141], v[194:197], v[92:95]
	v_mfma_f32_16x16x32_bf16 v[88:91], v[152:155], v[194:197], v[88:91]
	v_mfma_f32_16x16x32_bf16 v[76:79], v[138:141], v[202:205], v[76:79]
	v_mfma_f32_16x16x32_bf16 v[72:75], v[152:155], v[202:205], v[72:75]
	v_mfma_f32_16x16x32_bf16 v[124:127], v[148:151], v[180:183], v[124:127]
	v_mfma_f32_16x16x32_bf16 v[120:123], v[156:159], v[180:183], v[120:123]
	v_mfma_f32_16x16x32_bf16 v[108:111], v[148:151], v[188:191], v[108:111]
	v_mfma_f32_16x16x32_bf16 v[104:107], v[156:159], v[188:191], v[104:107]
	v_mfma_f32_16x16x32_bf16 v[92:95], v[148:151], v[198:201], v[92:95]
	v_mfma_f32_16x16x32_bf16 v[88:91], v[156:159], v[198:201], v[88:91]
	v_mfma_f32_16x16x32_bf16 v[76:79], v[148:151], v[206:209], v[76:79]
	v_mfma_f32_16x16x32_bf16 v[72:75], v[156:159], v[206:209], v[72:75]
	s_setprio 0
	s_setprio 1
	v_mfma_f32_16x16x32_bf16 v[116:119], v[160:163], v[176:179], v[116:119]
	v_mfma_f32_16x16x32_bf16 v[112:115], v[168:171], v[176:179], v[112:115]
	v_mfma_f32_16x16x32_bf16 v[100:103], v[160:163], v[184:187], v[100:103]
	v_mfma_f32_16x16x32_bf16 v[96:99], v[168:171], v[184:187], v[96:99]
	v_mfma_f32_16x16x32_bf16 v[84:87], v[160:163], v[194:197], v[84:87]
	v_mfma_f32_16x16x32_bf16 v[80:83], v[168:171], v[194:197], v[80:83]
	v_mfma_f32_16x16x32_bf16 v[68:71], v[160:163], v[202:205], v[68:71]
	v_mfma_f32_16x16x32_bf16 v[64:67], v[168:171], v[202:205], v[64:67]
	v_mfma_f32_16x16x32_bf16 v[116:119], v[164:167], v[180:183], v[116:119]
	v_mfma_f32_16x16x32_bf16 v[112:115], v[172:175], v[180:183], v[112:115]
	v_mfma_f32_16x16x32_bf16 v[100:103], v[164:167], v[188:191], v[100:103]
	v_mfma_f32_16x16x32_bf16 v[96:99], v[172:175], v[188:191], v[96:99]
	v_mfma_f32_16x16x32_bf16 v[84:87], v[164:167], v[198:201], v[84:87]
	v_mfma_f32_16x16x32_bf16 v[80:83], v[172:175], v[198:201], v[80:83]
	v_mfma_f32_16x16x32_bf16 v[68:71], v[164:167], v[206:209], v[68:71]
	v_mfma_f32_16x16x32_bf16 v[64:67], v[172:175], v[206:209], v[64:67]
	s_barrier
; #define PG8_STAGE(bufoff, gbase, voff) do { _Pragma("unroll") for (int _i = 0; _i < 2; ++_i) \
;         __builtin_amdgcn_global_load_lds((const unsigned*)((const char*)(gbase) + (voff)[_i]), (PG8_LAS unsigned*)(lds + (bufoff) + ldsw + _i * 8192), 16, 0, 0); } while (0)
; #define PG8_LDA(dst, b, h) do { _Pragma("unroll") for (int m = 0; m < 4; ++m) _Pragma("unroll") for (int k = 0; k < 2; ++k) dst[m][k] = *(const PG8_LAS bf16x8*)(lds + PG8_SA(b, h) + aoff + m * 2048 + k * 1024); } while (0)
; #define PG8_MMA(ai, bj, At, Bt) do { __builtin_amdgcn_s_setprio(1); _Pragma("unroll") for (int m = 0; m < 4; ++m) _Pragma("unroll") for (int n = 0; n < 2; ++n) _Pragma("unroll") for (int k = 0; k < 2; ++k) \
;         acc[ai][bj][m][n] = __builtin_amdgcn_mfma_f32_16x16x32_bf16(Bt[n][k], At[m][k], acc[ai][bj][m][n], 0, 0, 0); __builtin_amdgcn_s_setprio(0); } while (0)
; #define PG8_WAIT_V(n) asm volatile("s_waitcnt vmcnt(" #n ")" ::: "memory")
; #define PG8_WAIT_L(n) asm volatile("s_waitcnt lgkmcnt(" #n ")" ::: "memory")
; #define PG8_BAR __builtin_amdgcn_s_barrier()
; #define PG8_SCHED __builtin_amdgcn_sched_barrier(0)
; template <class Epi, class Sched, bool ALIGN_EPI = false, bool SP2 = false>
; __device__ __forceinline__ void gemm_phase(PG8_LAS unsigned char* lds, const Gemm g, const Sched& S, const Epi& E, int wid0) {
;     ...
;             PG8_LDA(At, 1, 1); PG8_STAGE(PG8_SB(1, 0), b3, voffB); PG8_STAGE(PG8_SB(1, 1), b3 + hstep, voffB); PG8_STAGE(PG8_SA(1, 0), a3, voffA);
;             PG8_WAIT_V(8); PG8_WAIT_L(0); PG8_BAR; PG8_MMA(1, 0, At, B0); PG8_MMA(1, 1, At, B1); PG8_BAR; PG8_SCHED;
;     ...
;         if constexpr (ALIGN_EPI) { if (wr == 0) PG8_BAR; }
	s_setprio 0
	s_add_i32 s26, s65, s69
	v_lshl_add_u64 v[210:211], v[210:211], 0, s[30:31]
	s_mov_b32 m0, s26
	ds_read_b128 v[176:179], v147 offset:49152
	ds_read_b128 v[180:183], v147 offset:50176
	ds_read_b128 v[184:187], v147 offset:51200
	ds_read_b128 v[188:191], v147 offset:52224
	ds_read_b128 v[194:197], v147 offset:53248
	ds_read_b128 v[198:201], v147 offset:54272
	ds_read_b128 v[202:205], v147 offset:55296
	ds_read_b128 v[206:209], v147 offset:56320
	global_load_lds_dwordx4 v[210:211], off
	s_add_i32 m0, s26, 0x2000
	s_add_u32 s26, s76, 0x40080
	v_lshl_add_u64 v[210:211], v[212:213], 0, s[30:31]
	s_addc_u32 s27, s77, 0
	s_add_i32 s65, s66, s69
	global_load_lds_dwordx4 v[210:211], off
	v_lshl_add_u64 v[210:211], s[26:27], 0, v[192:193]
	s_mov_b32 m0, s65
	s_nop 0
	global_load_lds_dwordx4 v[210:211], off
	v_lshl_add_u64 v[210:211], s[26:27], 0, v[132:133]
	s_add_i32 m0, s65, 0x2000
	s_nop 0
	global_load_lds_dwordx4 v[210:211], off
	v_lshl_add_u64 v[210:211], v[214:215], 0, s[30:31]
	s_mov_b32 m0, s92
	s_nop 0
	global_load_lds_dwordx4 v[210:211], off
	v_lshl_add_u64 v[210:211], v[220:221], 0, s[30:31]
	s_mov_b32 m0, s93
	s_nop 0
	global_load_lds_dwordx4 v[210:211], off
	s_waitcnt vmcnt(8)
	s_waitcnt lgkmcnt(0)
	s_barrier
	s_setprio 1
	v_mfma_f32_16x16x32_bf16 v[60:63], v[138:141], v[176:179], v[60:63]
	v_mfma_f32_16x16x32_bf16 v[56:59], v[152:155], v[176:179], v[56:59]
	v_mfma_f32_16x16x32_bf16 v[44:47], v[138:141], v[184:187], v[44:47]
	v_mfma_f32_16x16x32_bf16 v[40:43], v[152:155], v[184:187], v[40:43]
	v_mfma_f32_16x16x32_bf16 v[28:31], v[138:141], v[194:197], v[28:31]
	v_mfma_f32_16x16x32_bf16 v[24:27], v[152:155], v[194:197], v[24:27]
	v_mfma_f32_16x16x32_bf16 v[12:15], v[138:141], v[202:205], v[12:15]
	v_mfma_f32_16x16x32_bf16 v[8:11], v[152:155], v[202:205], v[8:11]
	v_mfma_f32_16x16x32_bf16 v[60:63], v[148:151], v[180:183], v[60:63]
	v_mfma_f32_16x16x32_bf16 v[56:59], v[156:159], v[180:183], v[56:59]
	v_mfma_f32_16x16x32_bf16 v[44:47], v[148:151], v[188:191], v[44:47]
	v_mfma_f32_16x16x32_bf16 v[40:43], v[156:159], v[188:191], v[40:43]
	v_mfma_f32_16x16x32_bf16 v[28:31], v[148:151], v[198:201], v[28:31]
	v_mfma_f32_16x16x32_bf16 v[24:27], v[156:159], v[198:201], v[24:27]
	v_mfma_f32_16x16x32_bf16 v[12:15], v[148:151], v[206:209], v[12:15]
	v_mfma_f32_16x16x32_bf16 v[8:11], v[156:159], v[206:209], v[8:11]
	s_setprio 0
	s_setprio 1
	v_mfma_f32_16x16x32_bf16 v[52:55], v[160:163], v[176:179], v[52:55]
	v_mfma_f32_16x16x32_bf16 v[48:51], v[168:171], v[176:179], v[48:51]
	v_mfma_f32_16x16x32_bf16 v[36:39], v[160:163], v[184:187], v[36:39]
	v_mfma_f32_16x16x32_bf16 v[32:35], v[168:171], v[184:187], v[32:35]
	v_mfma_f32_16x16x32_bf16 v[20:23], v[160:163], v[194:197], v[20:23]
	v_mfma_f32_16x16x32_bf16 v[16:19], v[168:171], v[194:197], v[16:19]
	v_mfma_f32_16x16x32_bf16 v[4:7], v[160:163], v[202:205], v[4:7]
	v_mfma_f32_16x16x32_bf16 v[0:3], v[168:171], v[202:205], v[0:3]
	v_mfma_f32_16x16x32_bf16 v[52:55], v[164:167], v[180:183], v[52:55]
	v_mfma_f32_16x16x32_bf16 v[48:51], v[172:175], v[180:183], v[48:51]
	v_mfma_f32_16x16x32_bf16 v[36:39], v[164:167], v[188:191], v[36:39]
	v_mfma_f32_16x16x32_bf16 v[32:35], v[172:175], v[188:191], v[32:35]
	v_mfma_f32_16x16x32_bf16 v[20:23], v[164:167], v[198:201], v[20:23]
	v_mfma_f32_16x16x32_bf16 v[16:19], v[172:175], v[198:201], v[16:19]
	v_mfma_f32_16x16x32_bf16 v[4:7], v[164:167], v[206:209], v[4:7]
	v_mfma_f32_16x16x32_bf16 v[0:3], v[172:175], v[206:209], v[0:3]
	s_barrier
	s_setprio 0
	s_add_i32 s64, s64, 2
	s_add_u32 s10, s10, 0x100
	s_addc_u32 s11, s11, 0
	s_add_u32 s84, s84, 0x100
	s_addc_u32 s85, s85, 0
	s_cmp_gt_u32 s64, 13
	s_cbranch_scc0 .LBB0_377
	s_and_b64 vcc, exec, s[70:71]
	s_cbranch_vccz .LBB0_380
	s_barrier

; #define PG8_STAGE(bufoff, gbase, voff) do { _Pragma("unroll") for (int _i = 0; _i < 2; ++_i) \
;         __builtin_amdgcn_global_load_lds((const unsigned*)((const char*)(gbase) + (voff)[_i]), (PG8_LAS unsigned*)(lds + (bufoff) + ldsw + _i * 8192), 16, 0, 0); } while (0)
; #define PG8_LDA(dst, b, h) do { _Pragma("unroll") for (int m = 0; m < 4; ++m) _Pragma("unroll") for (int k = 0; k < 2; ++k) dst[m][k] = *(const PG8_LAS bf16x8*)(lds + PG8_SA(b, h) + aoff + m * 2048 + k * 1024); } while (0)
; #define PG8_LDB(dst, b, h) do { _Pragma("unroll") for (int n = 0; n < 2; ++n) _Pragma("unroll") for (int k = 0; k < 2; ++k) dst[n][k] = *(const PG8_LAS bf16x8*)(lds + PG8_SB(b, h) + boff + n * 2048 + k * 1024); } while (0)
; #define PG8_MMA(ai, bj, At, Bt) do { __builtin_amdgcn_s_setprio(1); _Pragma("unroll") for (int m = 0; m < 4; ++m) _Pragma("unroll") for (int n = 0; n < 2; ++n) _Pragma("unroll") for (int k = 0; k < 2; ++k) \
;         acc[ai][bj][m][n] = __builtin_amdgcn_mfma_f32_16x16x32_bf16(Bt[n][k], At[m][k], acc[ai][bj][m][n], 0, 0, 0); __builtin_amdgcn_s_setprio(0); } while (0)
; #define PG8_WAIT_V(n) asm volatile("s_waitcnt vmcnt(" #n ")" ::: "memory")
; #define PG8_WAIT_L(n) asm volatile("s_waitcnt lgkmcnt(" #n ")" ::: "memory")
; #define PG8_BAR __builtin_amdgcn_s_barrier()
; #define PG8_SCHED __builtin_amdgcn_sched_barrier(0)
; template <class Epi, class Sched, bool ALIGN_EPI = false, bool SP2 = false>
; __device__ __forceinline__ void gemm_phase(PG8_LAS unsigned char* lds, const Gemm g, const Sched& S, const Epi& E, int wid0) {
;     ...
;             const bool last = (t == nt - 2);
;             const char* a1 = cA + (size_t)(t + 1) * kstep;
;             const char* a2 = last ? nA : cA + (size_t)(t + 2) * kstep; const char* b2 = last ? nB : cB + (size_t)(t + 2) * kstep;
;             const char* a3 = a2 + kstep; const char* b3 = b2 + kstep;
;             if (last && has_next) S.a_ready(nxt);
;             if constexpr (SP2) {
;             PG8_LDB(B0, 0, 0); PG8_LDB(B1, 0, 1); PG8_SCHED; PG8_LDA(At, 0, 0); PG8_STAGE(PG8_SA(1, 1), a1 + hstep, voffA);
;             PG8_WAIT_V(8); PG8_WAIT_L(0); PG8_BAR; PG8_MMA(0, 0, At, B0); PG8_MMA(0, 1, At, B1); PG8_BAR; PG8_SCHED;
;             PG8_LDA(At, 0, 1); PG8_STAGE(PG8_SB(0, 0), b2, voffB); PG8_STAGE(PG8_SB(0, 1), b2 + hstep, voffB); PG8_STAGE(PG8_SA(0, 0), a2, voffA);
.LBB0_544:
	s_add_i32 s65, 0, 0x10000
	v_add_u32_e32 v142, s65, v146
	s_add_i32 s66, 0, 0x14000
	ds_read_b128 v[138:141], v142
	ds_read_b128 v[150:153], v142 offset:1024
	ds_read_b128 v[154:157], v142 offset:2048
	ds_read_b128 v[158:161], v142 offset:3072
	v_add_u32_e32 v142, s66, v146
	ds_read_b128 v[162:165], v142
	ds_read_b128 v[166:169], v142 offset:1024
	ds_read_b128 v[170:173], v142 offset:2048
	ds_read_b128 v[174:177], v142 offset:3072
	v_lshl_add_u64 v[142:143], s[80:81], 0, v[136:137]
	s_add_i32 m0, s87, 0xc000
	ds_read_b128 v[178:181], v148
	ds_read_b128 v[182:185], v148 offset:1024
	ds_read_b128 v[186:189], v148 offset:2048
	ds_read_b128 v[194:197], v148 offset:3072
	ds_read_b128 v[198:201], v148 offset:4096
	ds_read_b128 v[202:205], v148 offset:5120
	ds_read_b128 v[206:209], v148 offset:6144
	ds_read_b128 v[210:213], v148 offset:7168
	global_load_lds_dwordx4 v[142:143], off
	v_lshl_add_u64 v[142:143], s[80:81], 0, v[134:135]
	s_add_i32 m0, s87, 0xe000
	s_nop 0
	global_load_lds_dwordx4 v[142:143], off
	s_add_u32 s26, s80, 0xfffc0080
	s_addc_u32 s27, s81, -1
	s_cmp_eq_u32 s64, 12
	s_cselect_b32 s85, s45, s27
	s_cselect_b32 s84, s73, s26
	s_cselect_b32 s83, s71, s11
	s_cselect_b32 s82, s79, s10
	s_waitcnt vmcnt(8)
	s_waitcnt lgkmcnt(0)
	s_barrier
	s_setprio 1
	v_mfma_f32_16x16x32_bf16 v[124:127], v[138:141], v[178:181], v[124:127]
	v_mfma_f32_16x16x32_bf16 v[116:119], v[154:157], v[178:181], v[116:119]
	v_mfma_f32_16x16x32_bf16 v[108:111], v[138:141], v[186:189], v[108:111]
	v_mfma_f32_16x16x32_bf16 v[100:103], v[154:157], v[186:189], v[100:103]
	v_mfma_f32_16x16x32_bf16 v[92:95], v[138:141], v[198:201], v[92:95]
	v_mfma_f32_16x16x32_bf16 v[84:87], v[154:157], v[198:201], v[84:87]
	v_mfma_f32_16x16x32_bf16 v[76:79], v[138:141], v[206:209], v[76:79]
	v_mfma_f32_16x16x32_bf16 v[68:71], v[154:157], v[206:209], v[68:71]
	v_mfma_f32_16x16x32_bf16 v[124:127], v[150:153], v[182:185], v[124:127]
	v_mfma_f32_16x16x32_bf16 v[116:119], v[158:161], v[182:185], v[116:119]
	v_mfma_f32_16x16x32_bf16 v[108:111], v[150:153], v[194:197], v[108:111]
	v_mfma_f32_16x16x32_bf16 v[100:103], v[158:161], v[194:197], v[100:103]
	v_mfma_f32_16x16x32_bf16 v[92:95], v[150:153], v[202:205], v[92:95]
	v_mfma_f32_16x16x32_bf16 v[84:87], v[158:161], v[202:205], v[84:87]
	v_mfma_f32_16x16x32_bf16 v[76:79], v[150:153], v[210:213], v[76:79]
	v_mfma_f32_16x16x32_bf16 v[68:71], v[158:161], v[210:213], v[68:71]
	s_setprio 0
	s_setprio 1
	v_mfma_f32_16x16x32_bf16 v[120:123], v[162:165], v[178:181], v[120:123]
	v_mfma_f32_16x16x32_bf16 v[112:115], v[170:173], v[178:181], v[112:115]
	v_mfma_f32_16x16x32_bf16 v[104:107], v[162:165], v[186:189], v[104:107]
	v_mfma_f32_16x16x32_bf16 v[96:99], v[170:173], v[186:189], v[96:99]
	v_mfma_f32_16x16x32_bf16 v[88:91], v[162:165], v[198:201], v[88:91]
	v_mfma_f32_16x16x32_bf16 v[80:83], v[170:173], v[198:201], v[80:83]
	v_mfma_f32_16x16x32_bf16 v[72:75], v[162:165], v[206:209], v[72:75]
	v_mfma_f32_16x16x32_bf16 v[64:67], v[170:173], v[206:209], v[64:67]
	v_mfma_f32_16x16x32_bf16 v[120:123], v[166:169], v[182:185], v[120:123]
	v_mfma_f32_16x16x32_bf16 v[112:115], v[174:177], v[182:185], v[112:115]
	v_mfma_f32_16x16x32_bf16 v[104:107], v[166:169], v[194:197], v[104:107]
	v_mfma_f32_16x16x32_bf16 v[96:99], v[174:177], v[194:197], v[96:99]
	v_mfma_f32_16x16x32_bf16 v[88:91], v[166:169], v[202:205], v[88:91]
	v_mfma_f32_16x16x32_bf16 v[80:83], v[174:177], v[202:205], v[80:83]
	v_mfma_f32_16x16x32_bf16 v[72:75], v[166:169], v[210:213], v[72:75]
	v_mfma_f32_16x16x32_bf16 v[64:67], v[174:177], v[210:213], v[64:67]
	s_barrier
	s_setprio 0
	s_add_i32 s26, s65, s86
	v_lshl_add_u64 v[142:143], s[82:83], 0, v[192:193]
	s_mov_b32 m0, s26
	ds_read_b128 v[178:181], v148 offset:16384
	ds_read_b128 v[182:185], v148 offset:17408
	ds_read_b128 v[186:189], v148 offset:18432
	ds_read_b128 v[194:197], v148 offset:19456
	ds_read_b128 v[198:201], v148 offset:20480
	ds_read_b128 v[202:205], v148 offset:21504
	ds_read_b128 v[206:209], v148 offset:22528
	ds_read_b128 v[210:213], v148 offset:23552
	global_load_lds_dwordx4 v[142:143], off
	s_add_i32 m0, s26, 0x2000
	s_add_u32 s26, s82, 0x40000
	v_lshl_add_u64 v[190:191], s[82:83], 0, v[128:129]
	s_addc_u32 s27, s83, 0
	s_add_i32 s65, s66, s86
	global_load_lds_dwordx4 v[190:191], off
	v_lshl_add_u64 v[214:215], s[26:27], 0, v[192:193]
	s_mov_b32 m0, s65
	v_lshl_add_u64 v[220:221], s[84:85], 0, v[130:131]
	global_load_lds_dwordx4 v[214:215], off
	v_lshl_add_u64 v[214:215], s[26:27], 0, v[128:129]
	s_add_i32 m0, s65, 0x2000
	s_nop 0
	global_load_lds_dwordx4 v[214:215], off
	v_lshl_add_u64 v[214:215], s[84:85], 0, v[132:133]
	s_mov_b32 m0, s87
	s_nop 0
	global_load_lds_dwordx4 v[214:215], off
	s_mov_b32 m0, s88
	s_nop 0
	global_load_lds_dwordx4 v[220:221], off
	s_waitcnt vmcnt(8)
	s_waitcnt lgkmcnt(0)
	s_barrier
; #define PG8_STAGE(bufoff, gbase, voff) do { _Pragma("unroll") for (int _i = 0; _i < 2; ++_i) \
;         __builtin_amdgcn_global_load_lds((const unsigned*)((const char*)(gbase) + (voff)[_i]), (PG8_LAS unsigned*)(lds + (bufoff) + ldsw + _i * 8192), 16, 0, 0); } while (0)
; #define PG8_LDA(dst, b, h) do { _Pragma("unroll") for (int m = 0; m < 4; ++m) _Pragma("unroll") for (int k = 0; k < 2; ++k) dst[m][k] = *(const PG8_LAS bf16x8*)(lds + PG8_SA(b, h) + aoff + m * 2048 + k * 1024); } while (0)
; #define PG8_LDB(dst, b, h) do { _Pragma("unroll") for (int n = 0; n < 2; ++n) _Pragma("unroll") for (int k = 0; k < 2; ++k) dst[n][k] = *(const PG8_LAS bf16x8*)(lds + PG8_SB(b, h) + boff + n * 2048 + k * 1024); } while (0)
; #define PG8_MMA(ai, bj, At, Bt) do { __builtin_amdgcn_s_setprio(1); _Pragma("unroll") for (int m = 0; m < 4; ++m) _Pragma("unroll") for (int n = 0; n < 2; ++n) _Pragma("unroll") for (int k = 0; k < 2; ++k) \
;         acc[ai][bj][m][n] = __builtin_amdgcn_mfma_f32_16x16x32_bf16(Bt[n][k], At[m][k], acc[ai][bj][m][n], 0, 0, 0); __builtin_amdgcn_s_setprio(0); } while (0)
; #define PG8_WAIT_V(n) asm volatile("s_waitcnt vmcnt(" #n ")" ::: "memory")
; #define PG8_WAIT_L(n) asm volatile("s_waitcnt lgkmcnt(" #n ")" ::: "memory")
; #define PG8_BAR __builtin_amdgcn_s_barrier()
; #define PG8_SCHED __builtin_amdgcn_sched_barrier(0)
; template <class Epi, class Sched, bool ALIGN_EPI = false, bool SP2 = false>
; __device__ __forceinline__ void gemm_phase(PG8_LAS unsigned char* lds, const Gemm g, const Sched& S, const Epi& E, int wid0) {
;     ...
;             PG8_WAIT_V(8); PG8_WAIT_L(0); PG8_BAR; PG8_MMA(1, 0, At, B0); PG8_MMA(1, 1, At, B1); PG8_BAR; PG8_SCHED;
;             PG8_LDB(B0, 1, 0); PG8_LDB(B1, 1, 1); PG8_SCHED; PG8_LDA(At, 1, 0); PG8_STAGE(PG8_SA(0, 1), a2 + hstep, voffA);
;             PG8_WAIT_V(8); PG8_WAIT_L(0); PG8_BAR; PG8_MMA(0, 0, At, B0); PG8_MMA(0, 1, At, B1); PG8_BAR; PG8_SCHED;
	s_setprio 1
	v_mfma_f32_16x16x32_bf16 v[60:63], v[138:141], v[178:181], v[60:63]
	v_mfma_f32_16x16x32_bf16 v[52:55], v[154:157], v[178:181], v[52:55]
	v_mfma_f32_16x16x32_bf16 v[44:47], v[138:141], v[186:189], v[44:47]
	v_mfma_f32_16x16x32_bf16 v[36:39], v[154:157], v[186:189], v[36:39]
	v_mfma_f32_16x16x32_bf16 v[28:31], v[138:141], v[198:201], v[28:31]
	v_mfma_f32_16x16x32_bf16 v[20:23], v[154:157], v[198:201], v[20:23]
	v_mfma_f32_16x16x32_bf16 v[12:15], v[138:141], v[206:209], v[12:15]
	v_mfma_f32_16x16x32_bf16 v[4:7], v[154:157], v[206:209], v[4:7]
	v_mfma_f32_16x16x32_bf16 v[60:63], v[150:153], v[182:185], v[60:63]
	v_mfma_f32_16x16x32_bf16 v[52:55], v[158:161], v[182:185], v[52:55]
	v_mfma_f32_16x16x32_bf16 v[44:47], v[150:153], v[194:197], v[44:47]
	v_mfma_f32_16x16x32_bf16 v[36:39], v[158:161], v[194:197], v[36:39]
	v_mfma_f32_16x16x32_bf16 v[28:31], v[150:153], v[202:205], v[28:31]
	v_mfma_f32_16x16x32_bf16 v[20:23], v[158:161], v[202:205], v[20:23]
	v_mfma_f32_16x16x32_bf16 v[12:15], v[150:153], v[210:213], v[12:15]
	v_mfma_f32_16x16x32_bf16 v[4:7], v[158:161], v[210:213], v[4:7]
	s_setprio 0
	s_setprio 1
	v_mfma_f32_16x16x32_bf16 v[56:59], v[162:165], v[178:181], v[56:59]
	v_mfma_f32_16x16x32_bf16 v[48:51], v[170:173], v[178:181], v[48:51]
	v_mfma_f32_16x16x32_bf16 v[40:43], v[162:165], v[186:189], v[40:43]
	v_mfma_f32_16x16x32_bf16 v[32:35], v[170:173], v[186:189], v[32:35]
	v_mfma_f32_16x16x32_bf16 v[24:27], v[162:165], v[198:201], v[24:27]
	v_mfma_f32_16x16x32_bf16 v[16:19], v[170:173], v[198:201], v[16:19]
	v_mfma_f32_16x16x32_bf16 v[8:11], v[162:165], v[206:209], v[8:11]
	v_mfma_f32_16x16x32_bf16 v[0:3], v[170:173], v[206:209], v[0:3]
	v_mfma_f32_16x16x32_bf16 v[56:59], v[166:169], v[182:185], v[56:59]
	v_mfma_f32_16x16x32_bf16 v[48:51], v[174:177], v[182:185], v[48:51]
	v_mfma_f32_16x16x32_bf16 v[40:43], v[166:169], v[194:197], v[40:43]
	v_mfma_f32_16x16x32_bf16 v[32:35], v[174:177], v[194:197], v[32:35]
	v_mfma_f32_16x16x32_bf16 v[24:27], v[166:169], v[202:205], v[24:27]
	v_mfma_f32_16x16x32_bf16 v[16:19], v[174:177], v[202:205], v[16:19]
	v_mfma_f32_16x16x32_bf16 v[8:11], v[166:169], v[210:213], v[8:11]
	v_mfma_f32_16x16x32_bf16 v[0:3], v[174:177], v[210:213], v[0:3]
	s_barrier
	s_setprio 0
	s_add_i32 s65, 0, 0x18000
	v_add_u32_e32 v144, s65, v146
	s_add_i32 s66, 0, 0x1c000
	ds_read_b128 v[138:141], v144
	ds_read_b128 v[150:153], v144 offset:1024
	ds_read_b128 v[154:157], v144 offset:2048
	ds_read_b128 v[158:161], v144 offset:3072
	v_add_u32_e32 v144, s66, v146
	ds_read_b128 v[162:165], v144
	ds_read_b128 v[166:169], v144 offset:1024
	ds_read_b128 v[170:173], v144 offset:2048
	ds_read_b128 v[174:177], v144 offset:3072
	s_add_u32 s26, s84, 0x40000
	s_addc_u32 s27, s85, 0
	s_mov_b32 m0, s89
	v_lshl_add_u64 v[222:223], s[26:27], 0, v[132:133]
	ds_read_b128 v[178:181], v148 offset:32768
	ds_read_b128 v[182:185], v148 offset:33792
	ds_read_b128 v[186:189], v148 offset:34816
	ds_read_b128 v[194:197], v148 offset:35840
	ds_read_b128 v[198:201], v148 offset:36864
	ds_read_b128 v[202:205], v148 offset:37888
	ds_read_b128 v[206:209], v148 offset:38912
	ds_read_b128 v[210:213], v148 offset:39936
	global_load_lds_dwordx4 v[222:223], off
	v_lshl_add_u64 v[222:223], s[26:27], 0, v[130:131]
	s_mov_b32 m0, s90
	s_nop 0
	global_load_lds_dwordx4 v[222:223], off
	s_waitcnt vmcnt(8)
	s_waitcnt lgkmcnt(0)
	s_barrier
	s_setprio 1
	v_mfma_f32_16x16x32_bf16 v[124:127], v[138:141], v[178:181], v[124:127]
	v_mfma_f32_16x16x32_bf16 v[116:119], v[154:157], v[178:181], v[116:119]
	v_mfma_f32_16x16x32_bf16 v[108:111], v[138:141], v[186:189], v[108:111]
	v_mfma_f32_16x16x32_bf16 v[100:103], v[154:157], v[186:189], v[100:103]
	v_mfma_f32_16x16x32_bf16 v[92:95], v[138:141], v[198:201], v[92:95]
	v_mfma_f32_16x16x32_bf16 v[84:87], v[154:157], v[198:201], v[84:87]
	v_mfma_f32_16x16x32_bf16 v[76:79], v[138:141], v[206:209], v[76:79]
	v_mfma_f32_16x16x32_bf16 v[68:71], v[154:157], v[206:209], v[68:71]
	v_mfma_f32_16x16x32_bf16 v[124:127], v[150:153], v[182:185], v[124:127]
	v_mfma_f32_16x16x32_bf16 v[116:119], v[158:161], v[182:185], v[116:119]
	v_mfma_f32_16x16x32_bf16 v[108:111], v[150:153], v[194:197], v[108:111]
	v_mfma_f32_16x16x32_bf16 v[100:103], v[158:161], v[194:197], v[100:103]
	v_mfma_f32_16x16x32_bf16 v[92:95], v[150:153], v[202:205], v[92:95]
	v_mfma_f32_16x16x32_bf16 v[84:87], v[158:161], v[202:205], v[84:87]
	v_mfma_f32_16x16x32_bf16 v[76:79], v[150:153], v[210:213], v[76:79]
	v_mfma_f32_16x16x32_bf16 v[68:71], v[158:161], v[210:213], v[68:71]
	s_setprio 0
	s_setprio 1
	v_mfma_f32_16x16x32_bf16 v[120:123], v[162:165], v[178:181], v[120:123]
	v_mfma_f32_16x16x32_bf16 v[112:115], v[170:173], v[178:181], v[112:115]
	v_mfma_f32_16x16x32_bf16 v[104:107], v[162:165], v[186:189], v[104:107]
	v_mfma_f32_16x16x32_bf16 v[96:99], v[170:173], v[186:189], v[96:99]
	v_mfma_f32_16x16x32_bf16 v[88:91], v[162:165], v[198:201], v[88:91]
	v_mfma_f32_16x16x32_bf16 v[80:83], v[170:173], v[198:201], v[80:83]
	v_mfma_f32_16x16x32_bf16 v[72:75], v[162:165], v[206:209], v[72:75]
	v_mfma_f32_16x16x32_bf16 v[64:67], v[170:173], v[206:209], v[64:67]
	v_mfma_f32_16x16x32_bf16 v[120:123], v[166:169], v[182:185], v[120:123]
	v_mfma_f32_16x16x32_bf16 v[112:115], v[174:177], v[182:185], v[112:115]
	v_mfma_f32_16x16x32_bf16 v[104:107], v[166:169], v[194:197], v[104:107]
	v_mfma_f32_16x16x32_bf16 v[96:99], v[174:177], v[194:197], v[96:99]
	v_mfma_f32_16x16x32_bf16 v[88:91], v[166:169], v[202:205], v[88:91]
	v_mfma_f32_16x16x32_bf16 v[80:83], v[174:177], v[202:205], v[80:83]
	v_mfma_f32_16x16x32_bf16 v[72:75], v[166:169], v[210:213], v[72:75]
	v_mfma_f32_16x16x32_bf16 v[64:67], v[174:177], v[210:213], v[64:67]
	s_barrier
; #define PG8_STAGE(bufoff, gbase, voff) do { _Pragma("unroll") for (int _i = 0; _i < 2; ++_i) \
;         __builtin_amdgcn_global_load_lds((const unsigned*)((const char*)(gbase) + (voff)[_i]), (PG8_LAS unsigned*)(lds + (bufoff) + ldsw + _i * 8192), 16, 0, 0); } while (0)
; #define PG8_LDA(dst, b, h) do { _Pragma("unroll") for (int m = 0; m < 4; ++m) _Pragma("unroll") for (int k = 0; k < 2; ++k) dst[m][k] = *(const PG8_LAS bf16x8*)(lds + PG8_SA(b, h) + aoff + m * 2048 + k * 1024); } while (0)
; #define PG8_MMA(ai, bj, At, Bt) do { __builtin_amdgcn_s_setprio(1); _Pragma("unroll") for (int m = 0; m < 4; ++m) _Pragma("unroll") for (int n = 0; n < 2; ++n) _Pragma("unroll") for (int k = 0; k < 2; ++k) \
;         acc[ai][bj][m][n] = __builtin_amdgcn_mfma_f32_16x16x32_bf16(Bt[n][k], At[m][k], acc[ai][bj][m][n], 0, 0, 0); __builtin_amdgcn_s_setprio(0); } while (0)
; #define PG8_WAIT_V(n) asm volatile("s_waitcnt vmcnt(" #n ")" ::: "memory")
; #define PG8_WAIT_L(n) asm volatile("s_waitcnt lgkmcnt(" #n ")" ::: "memory")
; #define PG8_BAR __builtin_amdgcn_s_barrier()
; #define PG8_SCHED __builtin_amdgcn_sched_barrier(0)
; template <class Epi, class Sched, bool ALIGN_EPI = false, bool SP2 = false>
; __device__ __forceinline__ void gemm_phase(PG8_LAS unsigned char* lds, const Gemm g, const Sched& S, const Epi& E, int wid0) {
;     ...
;             PG8_LDA(At, 1, 1); PG8_STAGE(PG8_SB(1, 0), b3, voffB); PG8_STAGE(PG8_SB(1, 1), b3 + hstep, voffB); PG8_STAGE(PG8_SA(1, 0), a3, voffA);
;             PG8_WAIT_V(8); PG8_WAIT_L(0); PG8_BAR; PG8_MMA(1, 0, At, B0); PG8_MMA(1, 1, At, B1); PG8_BAR; PG8_SCHED;
;     ...
;         if constexpr (ALIGN_EPI) { if (wr == 0) PG8_BAR; }
	s_setprio 0
	s_add_i32 s26, s65, s86
	v_lshl_add_u64 v[142:143], v[142:143], 0, s[30:31]
	s_mov_b32 m0, s26
	ds_read_b128 v[178:181], v148 offset:49152
	ds_read_b128 v[182:185], v148 offset:50176
	ds_read_b128 v[186:189], v148 offset:51200
	ds_read_b128 v[194:197], v148 offset:52224
	ds_read_b128 v[198:201], v148 offset:53248
	ds_read_b128 v[202:205], v148 offset:54272
	ds_read_b128 v[206:209], v148 offset:55296
	ds_read_b128 v[210:213], v148 offset:56320
	global_load_lds_dwordx4 v[142:143], off
	s_add_i32 m0, s26, 0x2000
	s_add_u32 s26, s82, 0x40080
	v_lshl_add_u64 v[142:143], v[190:191], 0, s[30:31]
	s_addc_u32 s27, s83, 0
	s_add_i32 s65, s66, s86
	global_load_lds_dwordx4 v[142:143], off
	v_lshl_add_u64 v[142:143], s[26:27], 0, v[192:193]
	s_mov_b32 m0, s65
	s_nop 0
	global_load_lds_dwordx4 v[142:143], off
	v_lshl_add_u64 v[142:143], s[26:27], 0, v[128:129]
	s_add_i32 m0, s65, 0x2000
	s_nop 0
	global_load_lds_dwordx4 v[142:143], off
	v_lshl_add_u64 v[142:143], v[214:215], 0, s[30:31]
	s_mov_b32 m0, s91
	s_nop 0
	global_load_lds_dwordx4 v[142:143], off
	v_lshl_add_u64 v[142:143], v[220:221], 0, s[30:31]
	s_mov_b32 m0, s92
	s_nop 0
	global_load_lds_dwordx4 v[142:143], off
	s_waitcnt vmcnt(8)
	s_waitcnt lgkmcnt(0)
	s_barrier
	s_setprio 1
	v_mfma_f32_16x16x32_bf16 v[60:63], v[138:141], v[178:181], v[60:63]
	v_mfma_f32_16x16x32_bf16 v[52:55], v[154:157], v[178:181], v[52:55]
	v_mfma_f32_16x16x32_bf16 v[44:47], v[138:141], v[186:189], v[44:47]
	v_mfma_f32_16x16x32_bf16 v[36:39], v[154:157], v[186:189], v[36:39]
	v_mfma_f32_16x16x32_bf16 v[28:31], v[138:141], v[198:201], v[28:31]
	v_mfma_f32_16x16x32_bf16 v[20:23], v[154:157], v[198:201], v[20:23]
	v_mfma_f32_16x16x32_bf16 v[12:15], v[138:141], v[206:209], v[12:15]
	v_mfma_f32_16x16x32_bf16 v[4:7], v[154:157], v[206:209], v[4:7]
	v_mfma_f32_16x16x32_bf16 v[60:63], v[150:153], v[182:185], v[60:63]
	v_mfma_f32_16x16x32_bf16 v[52:55], v[158:161], v[182:185], v[52:55]
	v_mfma_f32_16x16x32_bf16 v[44:47], v[150:153], v[194:197], v[44:47]
	v_mfma_f32_16x16x32_bf16 v[36:39], v[158:161], v[194:197], v[36:39]
	v_mfma_f32_16x16x32_bf16 v[28:31], v[150:153], v[202:205], v[28:31]
	v_mfma_f32_16x16x32_bf16 v[20:23], v[158:161], v[202:205], v[20:23]
	v_mfma_f32_16x16x32_bf16 v[12:15], v[150:153], v[210:213], v[12:15]
	v_mfma_f32_16x16x32_bf16 v[4:7], v[158:161], v[210:213], v[4:7]
	s_setprio 0
	s_setprio 1
	v_mfma_f32_16x16x32_bf16 v[56:59], v[162:165], v[178:181], v[56:59]
	v_mfma_f32_16x16x32_bf16 v[48:51], v[170:173], v[178:181], v[48:51]
	v_mfma_f32_16x16x32_bf16 v[40:43], v[162:165], v[186:189], v[40:43]
	v_mfma_f32_16x16x32_bf16 v[32:35], v[170:173], v[186:189], v[32:35]
	v_mfma_f32_16x16x32_bf16 v[24:27], v[162:165], v[198:201], v[24:27]
	v_mfma_f32_16x16x32_bf16 v[16:19], v[170:173], v[198:201], v[16:19]
	v_mfma_f32_16x16x32_bf16 v[8:11], v[162:165], v[206:209], v[8:11]
	v_mfma_f32_16x16x32_bf16 v[0:3], v[170:173], v[206:209], v[0:3]
	v_mfma_f32_16x16x32_bf16 v[56:59], v[166:169], v[182:185], v[56:59]
	v_mfma_f32_16x16x32_bf16 v[48:51], v[174:177], v[182:185], v[48:51]
	v_mfma_f32_16x16x32_bf16 v[40:43], v[166:169], v[194:197], v[40:43]
	v_mfma_f32_16x16x32_bf16 v[32:35], v[174:177], v[194:197], v[32:35]
	v_mfma_f32_16x16x32_bf16 v[24:27], v[166:169], v[202:205], v[24:27]
	v_mfma_f32_16x16x32_bf16 v[16:19], v[174:177], v[202:205], v[16:19]
	v_mfma_f32_16x16x32_bf16 v[8:11], v[166:169], v[210:213], v[8:11]
	v_mfma_f32_16x16x32_bf16 v[0:3], v[174:177], v[210:213], v[0:3]
	s_barrier
	s_setprio 0
	s_add_i32 s64, s64, 2
	s_add_u32 s10, s10, 0x100
	s_addc_u32 s11, s11, 0
	s_add_u32 s80, s80, 0x100
	s_addc_u32 s81, s81, 0
	s_cmp_gt_u32 s64, 13
	s_cbranch_scc0 .LBB0_544
	s_and_b64 vcc, exec, s[42:43]
	s_cbranch_vccz .LBB0_547
	s_barrier

; #define PG8_STAGE(bufoff, gbase, voff) do { _Pragma("unroll") for (int _i = 0; _i < 2; ++_i) \
;         __builtin_amdgcn_global_load_lds((const unsigned*)((const char*)(gbase) + (voff)[_i]), (PG8_LAS unsigned*)(lds + (bufoff) + ldsw + _i * 8192), 16, 0, 0); } while (0)
; #define PG8_LDA(dst, b, h) do { _Pragma("unroll") for (int m = 0; m < 4; ++m) _Pragma("unroll") for (int k = 0; k < 2; ++k) dst[m][k] = *(const PG8_LAS bf16x8*)(lds + PG8_SA(b, h) + aoff + m * 2048 + k * 1024); } while (0)
; #define PG8_LDB(dst, b, h) do { _Pragma("unroll") for (int n = 0; n < 2; ++n) _Pragma("unroll") for (int k = 0; k < 2; ++k) dst[n][k] = *(const PG8_LAS bf16x8*)(lds + PG8_SB(b, h) + boff + n * 2048 + k * 1024); } while (0)
; #define PG8_MMA(ai, bj, At, Bt) do { __builtin_amdgcn_s_setprio(1); _Pragma("unroll") for (int m = 0; m < 4; ++m) _Pragma("unroll") for (int n = 0; n < 2; ++n) _Pragma("unroll") for (int k = 0; k < 2; ++k) \
;         acc[ai][bj][m][n] = __builtin_amdgcn_mfma_f32_16x16x32_bf16(Bt[n][k], At[m][k], acc[ai][bj][m][n], 0, 0, 0); __builtin_amdgcn_s_setprio(0); } while (0)
; #define PG8_WAIT_V(n) asm volatile("s_waitcnt vmcnt(" #n ")" ::: "memory")
; #define PG8_WAIT_L(n) asm volatile("s_waitcnt lgkmcnt(" #n ")" ::: "memory")
; #define PG8_BAR __builtin_amdgcn_s_barrier()
; #define PG8_SCHED __builtin_amdgcn_sched_barrier(0)
; template <class Epi, class Sched, bool ALIGN_EPI = false, bool SP2 = false>
; __device__ __forceinline__ void gemm_phase(PG8_LAS unsigned char* lds, const Gemm g, const Sched& S, const Epi& E, int wid0) {
;     ...
;             const bool last = (t == nt - 2);
;             const char* a1 = cA + (size_t)(t + 1) * kstep;
;             const char* a2 = last ? nA : cA + (size_t)(t + 2) * kstep; const char* b2 = last ? nB : cB + (size_t)(t + 2) * kstep;
;             const char* a3 = a2 + kstep; const char* b3 = b2 + kstep;
;             if (last && has_next) S.a_ready(nxt);
;             if constexpr (SP2) {
;             PG8_LDB(B0, 0, 0); PG8_LDB(B1, 0, 1); PG8_SCHED; PG8_LDA(At, 0, 0); PG8_STAGE(PG8_SA(1, 1), a1 + hstep, voffA);
;             PG8_WAIT_V(8); PG8_WAIT_L(0); PG8_BAR; PG8_MMA(0, 0, At, B0); PG8_MMA(0, 1, At, B1); PG8_BAR; PG8_SCHED;
;             PG8_LDA(At, 0, 1); PG8_STAGE(PG8_SB(0, 0), b2, voffB); PG8_STAGE(PG8_SB(0, 1), b2 + hstep, voffB); PG8_STAGE(PG8_SA(0, 0), a2, voffA);
.LBB0_630:
	s_add_i32 s26, 0, 0x10000
	s_add_i32 s65, 0, 0x14000
	v_add_u32_e32 v156, s26, v143
	v_add_u32_e32 v172, s65, v143
	ds_read_b128 v[138:141], v156
	ds_read_b128 v[148:151], v156 offset:1024
	ds_read_b128 v[152:155], v156 offset:2048
	ds_read_b128 v[156:159], v156 offset:3072
	ds_read_b128 v[160:163], v172
	ds_read_b128 v[164:167], v172 offset:1024
	ds_read_b128 v[168:171], v172 offset:2048
	ds_read_b128 v[172:175], v172 offset:3072
	v_lshl_add_u64 v[210:211], s[76:77], 0, v[136:137]
	s_add_i32 m0, s84, 0xc000
	ds_read_b128 v[176:179], v147
	ds_read_b128 v[180:183], v147 offset:1024
	ds_read_b128 v[184:187], v147 offset:2048
	ds_read_b128 v[188:191], v147 offset:3072
	ds_read_b128 v[194:197], v147 offset:4096
	ds_read_b128 v[198:201], v147 offset:5120
	ds_read_b128 v[202:205], v147 offset:6144
	ds_read_b128 v[206:209], v147 offset:7168
	global_load_lds_dwordx4 v[210:211], off
	v_lshl_add_u64 v[210:211], s[76:77], 0, v[134:135]
	s_add_i32 m0, s84, 0xe000
	s_nop 0
	global_load_lds_dwordx4 v[210:211], off
	s_add_u32 s78, s76, 0x100
	s_addc_u32 s79, s77, 0
	s_cmp_eq_u32 s64, 40
	s_cselect_b32 s83, s43, s79
	s_cselect_b32 s82, s42, s78
	s_cselect_b32 s81, s75, s11
	s_cselect_b32 s80, s74, s10
	s_waitcnt vmcnt(8)
	s_waitcnt lgkmcnt(0)
	s_barrier
	s_setprio 1
	v_mfma_f32_16x16x32_bf16 v[124:127], v[138:141], v[176:179], v[124:127]
	v_mfma_f32_16x16x32_bf16 v[120:123], v[152:155], v[176:179], v[120:123]
	v_mfma_f32_16x16x32_bf16 v[108:111], v[138:141], v[184:187], v[108:111]
	v_mfma_f32_16x16x32_bf16 v[104:107], v[152:155], v[184:187], v[104:107]
	v_mfma_f32_16x16x32_bf16 v[92:95], v[138:141], v[194:197], v[92:95]
	v_mfma_f32_16x16x32_bf16 v[88:91], v[152:155], v[194:197], v[88:91]
	v_mfma_f32_16x16x32_bf16 v[76:79], v[138:141], v[202:205], v[76:79]
	v_mfma_f32_16x16x32_bf16 v[72:75], v[152:155], v[202:205], v[72:75]
	v_mfma_f32_16x16x32_bf16 v[124:127], v[148:151], v[180:183], v[124:127]
	v_mfma_f32_16x16x32_bf16 v[120:123], v[156:159], v[180:183], v[120:123]
	v_mfma_f32_16x16x32_bf16 v[108:111], v[148:151], v[188:191], v[108:111]
	v_mfma_f32_16x16x32_bf16 v[104:107], v[156:159], v[188:191], v[104:107]
	v_mfma_f32_16x16x32_bf16 v[92:95], v[148:151], v[198:201], v[92:95]
	v_mfma_f32_16x16x32_bf16 v[88:91], v[156:159], v[198:201], v[88:91]
	v_mfma_f32_16x16x32_bf16 v[76:79], v[148:151], v[206:209], v[76:79]
	v_mfma_f32_16x16x32_bf16 v[72:75], v[156:159], v[206:209], v[72:75]
	s_setprio 0
	s_setprio 1
	v_mfma_f32_16x16x32_bf16 v[116:119], v[160:163], v[176:179], v[116:119]
	v_mfma_f32_16x16x32_bf16 v[112:115], v[168:171], v[176:179], v[112:115]
	v_mfma_f32_16x16x32_bf16 v[100:103], v[160:163], v[184:187], v[100:103]
	v_mfma_f32_16x16x32_bf16 v[96:99], v[168:171], v[184:187], v[96:99]
	v_mfma_f32_16x16x32_bf16 v[84:87], v[160:163], v[194:197], v[84:87]
	v_mfma_f32_16x16x32_bf16 v[80:83], v[168:171], v[194:197], v[80:83]
	v_mfma_f32_16x16x32_bf16 v[68:71], v[160:163], v[202:205], v[68:71]
	v_mfma_f32_16x16x32_bf16 v[64:67], v[168:171], v[202:205], v[64:67]
	v_mfma_f32_16x16x32_bf16 v[116:119], v[164:167], v[180:183], v[116:119]
	v_mfma_f32_16x16x32_bf16 v[112:115], v[172:175], v[180:183], v[112:115]
	v_mfma_f32_16x16x32_bf16 v[100:103], v[164:167], v[188:191], v[100:103]
	v_mfma_f32_16x16x32_bf16 v[96:99], v[172:175], v[188:191], v[96:99]
	v_mfma_f32_16x16x32_bf16 v[84:87], v[164:167], v[198:201], v[84:87]
	v_mfma_f32_16x16x32_bf16 v[80:83], v[172:175], v[198:201], v[80:83]
	v_mfma_f32_16x16x32_bf16 v[68:71], v[164:167], v[206:209], v[68:71]
	v_mfma_f32_16x16x32_bf16 v[64:67], v[172:175], v[206:209], v[64:67]
	s_barrier
	s_setprio 0
	s_add_i32 s26, s26, s69
	v_lshl_add_u64 v[210:211], s[80:81], 0, v[192:193]
	s_mov_b32 m0, s26
	ds_read_b128 v[176:179], v147 offset:16384
	ds_read_b128 v[180:183], v147 offset:17408
	ds_read_b128 v[184:187], v147 offset:18432
	ds_read_b128 v[188:191], v147 offset:19456
	ds_read_b128 v[194:197], v147 offset:20480
	ds_read_b128 v[198:201], v147 offset:21504
	ds_read_b128 v[202:205], v147 offset:22528
	ds_read_b128 v[206:209], v147 offset:23552
	global_load_lds_dwordx4 v[210:211], off
	s_add_i32 m0, s26, 0x2000
	s_add_u32 s26, s80, 0xb0000
	v_lshl_add_u64 v[212:213], s[80:81], 0, v[132:133]
	s_addc_u32 s27, s81, 0
	s_add_i32 s65, s65, s69
	global_load_lds_dwordx4 v[212:213], off
	v_lshl_add_u64 v[214:215], s[26:27], 0, v[192:193]
	s_mov_b32 m0, s65
	v_lshl_add_u64 v[220:221], s[82:83], 0, v[130:131]
	global_load_lds_dwordx4 v[214:215], off
	v_lshl_add_u64 v[214:215], s[26:27], 0, v[132:133]
	s_add_i32 m0, s65, 0x2000
	s_nop 0
	global_load_lds_dwordx4 v[214:215], off
	v_lshl_add_u64 v[214:215], s[82:83], 0, v[128:129]
	s_mov_b32 m0, s84
	s_nop 0
	global_load_lds_dwordx4 v[214:215], off
	s_mov_b32 m0, s85
	s_nop 0
	global_load_lds_dwordx4 v[220:221], off
	s_waitcnt vmcnt(8)
	s_waitcnt lgkmcnt(0)
	s_barrier
; #define PG8_STAGE(bufoff, gbase, voff) do { _Pragma("unroll") for (int _i = 0; _i < 2; ++_i) \
;         __builtin_amdgcn_global_load_lds((const unsigned*)((const char*)(gbase) + (voff)[_i]), (PG8_LAS unsigned*)(lds + (bufoff) + ldsw + _i * 8192), 16, 0, 0); } while (0)
; #define PG8_LDA(dst, b, h) do { _Pragma("unroll") for (int m = 0; m < 4; ++m) _Pragma("unroll") for (int k = 0; k < 2; ++k) dst[m][k] = *(const PG8_LAS bf16x8*)(lds + PG8_SA(b, h) + aoff + m * 2048 + k * 1024); } while (0)
; #define PG8_LDB(dst, b, h) do { _Pragma("unroll") for (int n = 0; n < 2; ++n) _Pragma("unroll") for (int k = 0; k < 2; ++k) dst[n][k] = *(const PG8_LAS bf16x8*)(lds + PG8_SB(b, h) + boff + n * 2048 + k * 1024); } while (0)
; #define PG8_MMA(ai, bj, At, Bt) do { __builtin_amdgcn_s_setprio(1); _Pragma("unroll") for (int m = 0; m < 4; ++m) _Pragma("unroll") for (int n = 0; n < 2; ++n) _Pragma("unroll") for (int k = 0; k < 2; ++k) \
;         acc[ai][bj][m][n] = __builtin_amdgcn_mfma_f32_16x16x32_bf16(Bt[n][k], At[m][k], acc[ai][bj][m][n], 0, 0, 0); __builtin_amdgcn_s_setprio(0); } while (0)
; #define PG8_WAIT_V(n) asm volatile("s_waitcnt vmcnt(" #n ")" ::: "memory")
; #define PG8_WAIT_L(n) asm volatile("s_waitcnt lgkmcnt(" #n ")" ::: "memory")
; #define PG8_BAR __builtin_amdgcn_s_barrier()
; #define PG8_SCHED __builtin_amdgcn_sched_barrier(0)
; template <class Epi, class Sched, bool ALIGN_EPI = false, bool SP2 = false>
; __device__ __forceinline__ void gemm_phase(PG8_LAS unsigned char* lds, const Gemm g, const Sched& S, const Epi& E, int wid0) {
;     ...
;             PG8_WAIT_V(8); PG8_WAIT_L(0); PG8_BAR; PG8_MMA(1, 0, At, B0); PG8_MMA(1, 1, At, B1); PG8_BAR; PG8_SCHED;
;             PG8_LDB(B0, 1, 0); PG8_LDB(B1, 1, 1); PG8_SCHED; PG8_LDA(At, 1, 0); PG8_STAGE(PG8_SA(0, 1), a2 + hstep, voffA);
;             PG8_WAIT_V(8); PG8_WAIT_L(0); PG8_BAR; PG8_MMA(0, 0, At, B0); PG8_MMA(0, 1, At, B1); PG8_BAR; PG8_SCHED;
	s_setprio 1
	v_mfma_f32_16x16x32_bf16 v[60:63], v[138:141], v[176:179], v[60:63]
	v_mfma_f32_16x16x32_bf16 v[56:59], v[152:155], v[176:179], v[56:59]
	v_mfma_f32_16x16x32_bf16 v[44:47], v[138:141], v[184:187], v[44:47]
	v_mfma_f32_16x16x32_bf16 v[40:43], v[152:155], v[184:187], v[40:43]
	v_mfma_f32_16x16x32_bf16 v[28:31], v[138:141], v[194:197], v[28:31]
	v_mfma_f32_16x16x32_bf16 v[24:27], v[152:155], v[194:197], v[24:27]
	v_mfma_f32_16x16x32_bf16 v[12:15], v[138:141], v[202:205], v[12:15]
	v_mfma_f32_16x16x32_bf16 v[8:11], v[152:155], v[202:205], v[8:11]
	v_mfma_f32_16x16x32_bf16 v[60:63], v[148:151], v[180:183], v[60:63]
	v_mfma_f32_16x16x32_bf16 v[56:59], v[156:159], v[180:183], v[56:59]
	v_mfma_f32_16x16x32_bf16 v[44:47], v[148:151], v[188:191], v[44:47]
	v_mfma_f32_16x16x32_bf16 v[40:43], v[156:159], v[188:191], v[40:43]
	v_mfma_f32_16x16x32_bf16 v[28:31], v[148:151], v[198:201], v[28:31]
	v_mfma_f32_16x16x32_bf16 v[24:27], v[156:159], v[198:201], v[24:27]
	v_mfma_f32_16x16x32_bf16 v[12:15], v[148:151], v[206:209], v[12:15]
	v_mfma_f32_16x16x32_bf16 v[8:11], v[156:159], v[206:209], v[8:11]
	s_setprio 0
	s_setprio 1
	v_mfma_f32_16x16x32_bf16 v[52:55], v[160:163], v[176:179], v[52:55]
	v_mfma_f32_16x16x32_bf16 v[48:51], v[168:171], v[176:179], v[48:51]
	v_mfma_f32_16x16x32_bf16 v[36:39], v[160:163], v[184:187], v[36:39]
	v_mfma_f32_16x16x32_bf16 v[32:35], v[168:171], v[184:187], v[32:35]
	v_mfma_f32_16x16x32_bf16 v[20:23], v[160:163], v[194:197], v[20:23]
	v_mfma_f32_16x16x32_bf16 v[16:19], v[168:171], v[194:197], v[16:19]
	v_mfma_f32_16x16x32_bf16 v[4:7], v[160:163], v[202:205], v[4:7]
	v_mfma_f32_16x16x32_bf16 v[0:3], v[168:171], v[202:205], v[0:3]
	v_mfma_f32_16x16x32_bf16 v[52:55], v[164:167], v[180:183], v[52:55]
	v_mfma_f32_16x16x32_bf16 v[48:51], v[172:175], v[180:183], v[48:51]
	v_mfma_f32_16x16x32_bf16 v[36:39], v[164:167], v[188:191], v[36:39]
	v_mfma_f32_16x16x32_bf16 v[32:35], v[172:175], v[188:191], v[32:35]
	v_mfma_f32_16x16x32_bf16 v[20:23], v[164:167], v[198:201], v[20:23]
	v_mfma_f32_16x16x32_bf16 v[16:19], v[172:175], v[198:201], v[16:19]
	v_mfma_f32_16x16x32_bf16 v[4:7], v[164:167], v[206:209], v[4:7]
	v_mfma_f32_16x16x32_bf16 v[0:3], v[172:175], v[206:209], v[0:3]
	s_barrier
	s_setprio 0
	s_add_i32 s65, 0, 0x18000
	s_add_i32 s66, 0, 0x1c000
	v_add_u32_e32 v156, s65, v143
	v_add_u32_e32 v172, s66, v143
	ds_read_b128 v[138:141], v156
	ds_read_b128 v[148:151], v156 offset:1024
	ds_read_b128 v[152:155], v156 offset:2048
	ds_read_b128 v[156:159], v156 offset:3072
	ds_read_b128 v[160:163], v172
	ds_read_b128 v[164:167], v172 offset:1024
	ds_read_b128 v[168:171], v172 offset:2048
	ds_read_b128 v[172:175], v172 offset:3072
	s_add_u32 s26, s82, 0xb0000
	s_addc_u32 s27, s83, 0
	s_mov_b32 m0, s86
	v_lshl_add_u64 v[222:223], s[26:27], 0, v[128:129]
	ds_read_b128 v[176:179], v147 offset:32768
	ds_read_b128 v[180:183], v147 offset:33792
	ds_read_b128 v[184:187], v147 offset:34816
	ds_read_b128 v[188:191], v147 offset:35840
	ds_read_b128 v[194:197], v147 offset:36864
	ds_read_b128 v[198:201], v147 offset:37888
	ds_read_b128 v[202:205], v147 offset:38912
	ds_read_b128 v[206:209], v147 offset:39936
	global_load_lds_dwordx4 v[222:223], off
	v_lshl_add_u64 v[222:223], s[26:27], 0, v[130:131]
	s_mov_b32 m0, s87
	s_nop 0
	global_load_lds_dwordx4 v[222:223], off
	s_waitcnt vmcnt(8)
	s_waitcnt lgkmcnt(0)
	s_barrier
	s_setprio 1
	v_mfma_f32_16x16x32_bf16 v[124:127], v[138:141], v[176:179], v[124:127]
	v_mfma_f32_16x16x32_bf16 v[120:123], v[152:155], v[176:179], v[120:123]
	v_mfma_f32_16x16x32_bf16 v[108:111], v[138:141], v[184:187], v[108:111]
	v_mfma_f32_16x16x32_bf16 v[104:107], v[152:155], v[184:187], v[104:107]
	v_mfma_f32_16x16x32_bf16 v[92:95], v[138:141], v[194:197], v[92:95]
	v_mfma_f32_16x16x32_bf16 v[88:91], v[152:155], v[194:197], v[88:91]
	v_mfma_f32_16x16x32_bf16 v[76:79], v[138:141], v[202:205], v[76:79]
	v_mfma_f32_16x16x32_bf16 v[72:75], v[152:155], v[202:205], v[72:75]
	v_mfma_f32_16x16x32_bf16 v[124:127], v[148:151], v[180:183], v[124:127]
	v_mfma_f32_16x16x32_bf16 v[120:123], v[156:159], v[180:183], v[120:123]
	v_mfma_f32_16x16x32_bf16 v[108:111], v[148:151], v[188:191], v[108:111]
	v_mfma_f32_16x16x32_bf16 v[104:107], v[156:159], v[188:191], v[104:107]
	v_mfma_f32_16x16x32_bf16 v[92:95], v[148:151], v[198:201], v[92:95]
	v_mfma_f32_16x16x32_bf16 v[88:91], v[156:159], v[198:201], v[88:91]
	v_mfma_f32_16x16x32_bf16 v[76:79], v[148:151], v[206:209], v[76:79]
	v_mfma_f32_16x16x32_bf16 v[72:75], v[156:159], v[206:209], v[72:75]
	s_setprio 0
	s_setprio 1
	v_mfma_f32_16x16x32_bf16 v[116:119], v[160:163], v[176:179], v[116:119]
	v_mfma_f32_16x16x32_bf16 v[112:115], v[168:171], v[176:179], v[112:115]
	v_mfma_f32_16x16x32_bf16 v[100:103], v[160:163], v[184:187], v[100:103]
	v_mfma_f32_16x16x32_bf16 v[96:99], v[168:171], v[184:187], v[96:99]
	v_mfma_f32_16x16x32_bf16 v[84:87], v[160:163], v[194:197], v[84:87]
	v_mfma_f32_16x16x32_bf16 v[80:83], v[168:171], v[194:197], v[80:83]
	v_mfma_f32_16x16x32_bf16 v[68:71], v[160:163], v[202:205], v[68:71]
	v_mfma_f32_16x16x32_bf16 v[64:67], v[168:171], v[202:205], v[64:67]
	v_mfma_f32_16x16x32_bf16 v[116:119], v[164:167], v[180:183], v[116:119]
	v_mfma_f32_16x16x32_bf16 v[112:115], v[172:175], v[180:183], v[112:115]
	v_mfma_f32_16x16x32_bf16 v[100:103], v[164:167], v[188:191], v[100:103]
	v_mfma_f32_16x16x32_bf16 v[96:99], v[172:175], v[188:191], v[96:99]
	v_mfma_f32_16x16x32_bf16 v[84:87], v[164:167], v[198:201], v[84:87]
	v_mfma_f32_16x16x32_bf16 v[80:83], v[172:175], v[198:201], v[80:83]
	v_mfma_f32_16x16x32_bf16 v[68:71], v[164:167], v[206:209], v[68:71]
	v_mfma_f32_16x16x32_bf16 v[64:67], v[172:175], v[206:209], v[64:67]
	s_barrier
; #define PG8_STAGE(bufoff, gbase, voff) do { _Pragma("unroll") for (int _i = 0; _i < 2; ++_i) \
;         __builtin_amdgcn_global_load_lds((const unsigned*)((const char*)(gbase) + (voff)[_i]), (PG8_LAS unsigned*)(lds + (bufoff) + ldsw + _i * 8192), 16, 0, 0); } while (0)
; #define PG8_LDA(dst, b, h) do { _Pragma("unroll") for (int m = 0; m < 4; ++m) _Pragma("unroll") for (int k = 0; k < 2; ++k) dst[m][k] = *(const PG8_LAS bf16x8*)(lds + PG8_SA(b, h) + aoff + m * 2048 + k * 1024); } while (0)
; #define PG8_MMA(ai, bj, At, Bt) do { __builtin_amdgcn_s_setprio(1); _Pragma("unroll") for (int m = 0; m < 4; ++m) _Pragma("unroll") for (int n = 0; n < 2; ++n) _Pragma("unroll") for (int k = 0; k < 2; ++k) \
;         acc[ai][bj][m][n] = __builtin_amdgcn_mfma_f32_16x16x32_bf16(Bt[n][k], At[m][k], acc[ai][bj][m][n], 0, 0, 0); __builtin_amdgcn_s_setprio(0); } while (0)
; #define PG8_WAIT_V(n) asm volatile("s_waitcnt vmcnt(" #n ")" ::: "memory")
; #define PG8_WAIT_L(n) asm volatile("s_waitcnt lgkmcnt(" #n ")" ::: "memory")
; #define PG8_BAR __builtin_amdgcn_s_barrier()
; #define PG8_SCHED __builtin_amdgcn_sched_barrier(0)
; template <class Epi, class Sched, bool ALIGN_EPI = false, bool SP2 = false>
; __device__ __forceinline__ void gemm_phase(PG8_LAS unsigned char* lds, const Gemm g, const Sched& S, const Epi& E, int wid0) {
;     ...
;             PG8_LDA(At, 1, 1); PG8_STAGE(PG8_SB(1, 0), b3, voffB); PG8_STAGE(PG8_SB(1, 1), b3 + hstep, voffB); PG8_STAGE(PG8_SA(1, 0), a3, voffA);
;             PG8_WAIT_V(8); PG8_WAIT_L(0); PG8_BAR; PG8_MMA(1, 0, At, B0); PG8_MMA(1, 1, At, B1); PG8_BAR; PG8_SCHED;
;     ...
;         if constexpr (ALIGN_EPI) { if (wr == 0) PG8_BAR; }
	s_setprio 0
	s_add_i32 s26, s65, s69
	v_lshl_add_u64 v[210:211], v[210:211], 0, s[30:31]
	s_mov_b32 m0, s26
	ds_read_b128 v[176:179], v147 offset:49152
	ds_read_b128 v[180:183], v147 offset:50176
	ds_read_b128 v[184:187], v147 offset:51200
	ds_read_b128 v[188:191], v147 offset:52224
	ds_read_b128 v[194:197], v147 offset:53248
	ds_read_b128 v[198:201], v147 offset:54272
	ds_read_b128 v[202:205], v147 offset:55296
	ds_read_b128 v[206:209], v147 offset:56320
	global_load_lds_dwordx4 v[210:211], off
	s_add_i32 m0, s26, 0x2000
	s_add_u32 s26, s80, 0xb0080
	v_lshl_add_u64 v[210:211], v[212:213], 0, s[30:31]
	s_addc_u32 s27, s81, 0
	s_add_i32 s65, s66, s69
	global_load_lds_dwordx4 v[210:211], off
	v_lshl_add_u64 v[210:211], s[26:27], 0, v[192:193]
	s_mov_b32 m0, s65
	s_nop 0
	global_load_lds_dwordx4 v[210:211], off
	v_lshl_add_u64 v[210:211], s[26:27], 0, v[132:133]
	s_add_i32 m0, s65, 0x2000
	s_nop 0
	global_load_lds_dwordx4 v[210:211], off
	v_lshl_add_u64 v[210:211], v[214:215], 0, s[30:31]
	s_mov_b32 m0, s89
	s_nop 0
	global_load_lds_dwordx4 v[210:211], off
	v_lshl_add_u64 v[210:211], v[220:221], 0, s[30:31]
	s_mov_b32 m0, s90
	s_nop 0
	global_load_lds_dwordx4 v[210:211], off
	s_waitcnt vmcnt(8)
	s_waitcnt lgkmcnt(0)
	s_barrier
	s_setprio 1
	v_mfma_f32_16x16x32_bf16 v[60:63], v[138:141], v[176:179], v[60:63]
	v_mfma_f32_16x16x32_bf16 v[56:59], v[152:155], v[176:179], v[56:59]
	v_mfma_f32_16x16x32_bf16 v[44:47], v[138:141], v[184:187], v[44:47]
	v_mfma_f32_16x16x32_bf16 v[40:43], v[152:155], v[184:187], v[40:43]
	v_mfma_f32_16x16x32_bf16 v[28:31], v[138:141], v[194:197], v[28:31]
	v_mfma_f32_16x16x32_bf16 v[24:27], v[152:155], v[194:197], v[24:27]
	v_mfma_f32_16x16x32_bf16 v[12:15], v[138:141], v[202:205], v[12:15]
	v_mfma_f32_16x16x32_bf16 v[8:11], v[152:155], v[202:205], v[8:11]
	v_mfma_f32_16x16x32_bf16 v[60:63], v[148:151], v[180:183], v[60:63]
	v_mfma_f32_16x16x32_bf16 v[56:59], v[156:159], v[180:183], v[56:59]
	v_mfma_f32_16x16x32_bf16 v[44:47], v[148:151], v[188:191], v[44:47]
	v_mfma_f32_16x16x32_bf16 v[40:43], v[156:159], v[188:191], v[40:43]
	v_mfma_f32_16x16x32_bf16 v[28:31], v[148:151], v[198:201], v[28:31]
	v_mfma_f32_16x16x32_bf16 v[24:27], v[156:159], v[198:201], v[24:27]
	v_mfma_f32_16x16x32_bf16 v[12:15], v[148:151], v[206:209], v[12:15]
	v_mfma_f32_16x16x32_bf16 v[8:11], v[156:159], v[206:209], v[8:11]
	s_setprio 0
	s_setprio 1
	v_mfma_f32_16x16x32_bf16 v[52:55], v[160:163], v[176:179], v[52:55]
	v_mfma_f32_16x16x32_bf16 v[48:51], v[168:171], v[176:179], v[48:51]
	v_mfma_f32_16x16x32_bf16 v[36:39], v[160:163], v[184:187], v[36:39]
	v_mfma_f32_16x16x32_bf16 v[32:35], v[168:171], v[184:187], v[32:35]
	v_mfma_f32_16x16x32_bf16 v[20:23], v[160:163], v[194:197], v[20:23]
	v_mfma_f32_16x16x32_bf16 v[16:19], v[168:171], v[194:197], v[16:19]
	v_mfma_f32_16x16x32_bf16 v[4:7], v[160:163], v[202:205], v[4:7]
	v_mfma_f32_16x16x32_bf16 v[0:3], v[168:171], v[202:205], v[0:3]
	v_mfma_f32_16x16x32_bf16 v[52:55], v[164:167], v[180:183], v[52:55]
	v_mfma_f32_16x16x32_bf16 v[48:51], v[172:175], v[180:183], v[48:51]
	v_mfma_f32_16x16x32_bf16 v[36:39], v[164:167], v[188:191], v[36:39]
	v_mfma_f32_16x16x32_bf16 v[32:35], v[172:175], v[188:191], v[32:35]
	v_mfma_f32_16x16x32_bf16 v[20:23], v[164:167], v[198:201], v[20:23]
	v_mfma_f32_16x16x32_bf16 v[16:19], v[172:175], v[198:201], v[16:19]
	v_mfma_f32_16x16x32_bf16 v[4:7], v[164:167], v[206:209], v[4:7]
	v_mfma_f32_16x16x32_bf16 v[0:3], v[172:175], v[206:209], v[0:3]
	s_barrier
	s_setprio 0
	s_add_i32 s64, s64, 2
	s_add_u32 s10, s10, 0x100
	s_addc_u32 s11, s11, 0
	s_cmp_gt_u32 s64, 41
	s_mov_b64 s[76:77], s[78:79]
	s_cbranch_scc0 .LBB0_630
	s_and_b64 vcc, exec, s[72:73]
	s_cbranch_vccz .LBB0_633
	s_barrier
